# attention branch 0 via shared LDS stage with streamed K fragments; branch-1 prefetch issued before branch 0's score phase
# baseline (speedup 1.0000x reference)
.Latt_unit:
	s_mov_b32 s33, s12
	s_mov_b32 s34, s15
	s_mov_b32 s35, s16
	s_mov_b32 s36, s17
	s_mov_b32 s38, s14
	s_mov_b32 s39, s13
	s_mov_b32 s24, s20
	s_mov_b32 s25, s21
	s_mov_b32 s26, s22
	s_mov_b32 s27, s23
	s_mov_b32 s40, s42
	s_mov_b32 s41, s43
	v_mov_b32_e32 v173, v176
	v_mov_b32_e32 v174, v177
	v_mov_b32_e32 v175, v178
	v_mov_b32_e32 v179, v183
	v_mov_b32_e32 v182, v252
	s_lshr_b32 s44, s33, 0
	s_lshr_b32 s2, s0, 2
	s_lshl_b32 s2, s2, 5
	s_lshr_b32 s3, s15, 2
	s_add_i32 s42, s3, s2
	s_and_b32 s43, s0, 3
	s_waitcnt vmcnt(4)
	ds_write_b128 v253, v[0:3]
	ds_write_b128 v253, v[4:7] offset:1152
	ds_write_b128 v253, v[8:11] offset:2304
	ds_write_b128 v253, v[12:15] offset:3456
	ds_write_b128 v253, v[16:19] offset:4608
	ds_write_b128 v253, v[20:23] offset:5760
	ds_write_b128 v253, v[24:27] offset:55296
	ds_write_b128 v253, v[28:31] offset:56448
	ds_write_b128 v253, v[32:35] offset:57600
	ds_write_b128 v253, v[36:39] offset:58752
	ds_write_b128 v253, v[40:43] offset:59904
	ds_write_b128 v253, v[44:47] offset:61056
	s_waitcnt lgkmcnt(0)
	s_barrier
	v_add_u32_e32 v134, s42, v160
	v_lshlrev_b32_e32 v134, 2, v134
	v_add_u32_e32 v134, s43, v134
	v_subrev_u32_e32 v135, s15, v134
	v_lshrrev_b32_e32 v136, 4, v135
	v_add_u32_e32 v136, v136, v135
	v_mad_u32_u24 v176, v136, s79, v161
	v_lshl_add_u32 v177, v135, 2, s80
	s_sub_i32 s2, s42, 64
	v_add_u32_e32 v178, s2, v169
	v_and_b32_e32 v135, 3, v134
	v_lshlrev_b32_e32 v135, s13, v135
	v_lshrrev_b32_e32 v136, 2, v134
	v_add_u32_e32 v135, v135, v136
	v_lshl_add_u32 v143, v135, 7, v161
	v_add_u32_e32 v137, 64, v134
	v_and_b32_e32 v135, 3, v137
	v_lshlrev_b32_e32 v135, s13, v135
	v_lshrrev_b32_e32 v136, 2, v137
	v_add_u32_e32 v135, v135, v136
	v_lshl_add_u32 v147, v135, 7, v161
	v_subrev_u32_e32 v134, 0x100, v134
	v_and_b32_e32 v137, 3, v134
	v_lshlrev_b32_e32 v137, s13, v137
	v_bfe_u32 v135, v134, 2, 2
	v_add_u32_e32 v137, v137, v135
	v_lshl_add_u32 v183, v137, 7, v161
	v_ashrrev_i32_e32 v252, 4, v134
	v_med3_i32 v136, v252, 0, s14
	v_lshl_add_u32 v136, v136, 9, v183
	global_load_dwordx4 v[0:3], v136, s[20:21]
	global_load_dwordx4 v[4:7], v136, s[20:21] offset:64
	v_add_u32_e32 v135, 4, v252
	v_med3_i32 v135, v135, 0, s14
	v_lshl_add_u32 v135, v135, 9, v183
	global_load_dwordx4 v[8:11], v135, s[20:21]
	global_load_dwordx4 v[12:15], v135, s[20:21] offset:64
	v_add_u32_e32 v136, 8, v252
	v_med3_i32 v136, v136, 0, s14
	v_lshl_add_u32 v136, v136, 9, v183
	global_load_dwordx4 v[16:19], v136, s[20:21]
	global_load_dwordx4 v[20:23], v136, s[20:21] offset:64
	v_add_u32_e32 v135, 12, v252
	v_med3_i32 v135, v135, 0, s14
	v_lshl_add_u32 v135, v135, 9, v183
	global_load_dwordx4 v[24:27], v135, s[20:21]
	global_load_dwordx4 v[28:31], v135, s[20:21] offset:64
	v_add_u32_e32 v136, 16, v252
	v_med3_i32 v136, v136, 0, s14
	v_lshl_add_u32 v136, v136, 9, v183
	global_load_dwordx4 v[32:35], v136, s[20:21]
	global_load_dwordx4 v[36:39], v136, s[20:21] offset:64
	v_add_u32_e32 v135, 20, v252
	v_med3_i32 v135, v135, 0, s14
	v_lshl_add_u32 v135, v135, 9, v183
	global_load_dwordx4 v[40:43], v135, s[20:21]
	global_load_dwordx4 v[44:47], v135, s[20:21] offset:64
	s_add_i32 s2, s42, -64
	v_add_u32_e32 v138, s2, v164
	v_lshlrev_b32_e32 v138, 2, v138
	v_add_u32_e32 v138, s43, v138
	v_and_b32_e32 v139, 3, v138
	v_lshlrev_b32_e32 v139, s13, v139
	v_bfe_u32 v140, v138, 2, 2
	v_add_u32_e32 v139, v139, v140
	v_lshl_add_u32 v139, v139, 7, v162
	v_ashrrev_i32_e32 v138, 4, v138
	v_med3_i32 v138, v138, 0, s14
	v_lshl_add_u32 v138, v138, 9, v139
	global_load_dwordx4 v[64:67], v138, s[22:23]
	s_add_i32 s2, s42, -56
	v_add_u32_e32 v138, s2, v164
	v_lshlrev_b32_e32 v138, 2, v138
	v_add_u32_e32 v138, s43, v138
	v_and_b32_e32 v139, 3, v138
	v_lshlrev_b32_e32 v139, s13, v139
	v_bfe_u32 v140, v138, 2, 2
	v_add_u32_e32 v139, v139, v140
	v_lshl_add_u32 v139, v139, 7, v162
	v_ashrrev_i32_e32 v138, 4, v138
	v_med3_i32 v138, v138, 0, s14
	v_lshl_add_u32 v138, v138, 9, v139
	global_load_dwordx4 v[68:71], v138, s[22:23]
	s_add_i32 s2, s42, -48
	v_add_u32_e32 v138, s2, v164
	v_lshlrev_b32_e32 v138, 2, v138
	v_add_u32_e32 v138, s43, v138
	v_and_b32_e32 v139, 3, v138
	v_lshlrev_b32_e32 v139, s13, v139
	v_bfe_u32 v140, v138, 2, 2
	v_add_u32_e32 v139, v139, v140
	v_lshl_add_u32 v139, v139, 7, v162
	v_ashrrev_i32_e32 v138, 4, v138
	v_med3_i32 v138, v138, 0, s14
	v_lshl_add_u32 v138, v138, 9, v139
	global_load_dwordx4 v[72:75], v138, s[22:23]
	s_add_i32 s2, s42, -40
	v_add_u32_e32 v138, s2, v164
	v_lshlrev_b32_e32 v138, 2, v138
	v_add_u32_e32 v138, s43, v138
	v_and_b32_e32 v139, 3, v138
	v_lshlrev_b32_e32 v139, s13, v139
	v_bfe_u32 v140, v138, 2, 2
	v_add_u32_e32 v139, v139, v140
	v_lshl_add_u32 v139, v139, 7, v162
	v_ashrrev_i32_e32 v138, 4, v138
	v_med3_i32 v138, v138, 0, s14
	v_lshl_add_u32 v138, v138, 9, v139
	global_load_dwordx4 v[76:79], v138, s[22:23]
	s_add_i32 s2, s42, -32
	v_add_u32_e32 v138, s2, v164
	v_lshlrev_b32_e32 v138, 2, v138
	v_add_u32_e32 v138, s43, v138
	v_and_b32_e32 v139, 3, v138
	v_lshlrev_b32_e32 v139, s13, v139
	v_bfe_u32 v140, v138, 2, 2
	v_add_u32_e32 v139, v139, v140
	v_lshl_add_u32 v139, v139, 7, v162
	v_ashrrev_i32_e32 v138, 4, v138
	v_med3_i32 v138, v138, 0, s14
	v_lshl_add_u32 v138, v138, 9, v139
	global_load_dwordx4 v[80:83], v138, s[22:23]
	s_add_i32 s2, s42, -24
	v_add_u32_e32 v138, s2, v164
	v_lshlrev_b32_e32 v138, 2, v138
	v_add_u32_e32 v138, s43, v138
	v_and_b32_e32 v139, 3, v138
	v_lshlrev_b32_e32 v139, s13, v139
	v_bfe_u32 v140, v138, 2, 2
	v_add_u32_e32 v139, v139, v140
	v_lshl_add_u32 v139, v139, 7, v162
	v_ashrrev_i32_e32 v138, 4, v138
	v_med3_i32 v138, v138, 0, s14
	v_lshl_add_u32 v138, v138, 9, v139
	global_load_dwordx4 v[84:87], v138, s[22:23]
	s_add_i32 s2, s42, -16
	v_add_u32_e32 v138, s2, v164
	v_lshlrev_b32_e32 v138, 2, v138
	v_add_u32_e32 v138, s43, v138
	v_and_b32_e32 v139, 3, v138
	v_lshlrev_b32_e32 v139, s13, v139
	v_bfe_u32 v140, v138, 2, 2
	v_add_u32_e32 v139, v139, v140
	v_lshl_add_u32 v139, v139, 7, v162
	v_ashrrev_i32_e32 v138, 4, v138
	v_med3_i32 v138, v138, 0, s14
	v_lshl_add_u32 v138, v138, 9, v139
	global_load_dwordx4 v[88:91], v138, s[22:23]
	s_add_i32 s2, s42, -8
	v_add_u32_e32 v138, s2, v164
	v_lshlrev_b32_e32 v138, 2, v138
	v_add_u32_e32 v138, s43, v138
	v_and_b32_e32 v139, 3, v138
	v_lshlrev_b32_e32 v139, s13, v139
	v_bfe_u32 v140, v138, 2, 2
	v_add_u32_e32 v139, v139, v140
	v_lshl_add_u32 v139, v139, 7, v162
	v_ashrrev_i32_e32 v138, 4, v138
	v_med3_i32 v138, v138, 0, s14
	v_lshl_add_u32 v138, v138, 9, v139
	global_load_dwordx4 v[92:95], v138, s[22:23]
	s_add_i32 s2, s42, 0
	v_add_u32_e32 v138, s2, v164
	v_lshlrev_b32_e32 v138, 2, v138
	v_add_u32_e32 v138, s43, v138
	v_and_b32_e32 v139, 3, v138
	v_lshlrev_b32_e32 v139, s13, v139
	v_bfe_u32 v140, v138, 2, 2
	v_add_u32_e32 v139, v139, v140
	v_lshl_add_u32 v139, v139, 7, v162
	v_ashrrev_i32_e32 v138, 4, v138
	v_med3_i32 v138, v138, 0, s14
	v_lshl_add_u32 v138, v138, 9, v139
	global_load_dwordx4 v[96:99], v138, s[22:23]
	s_add_i32 s2, s42, 8
	v_add_u32_e32 v138, s2, v164
	v_lshlrev_b32_e32 v138, 2, v138
	v_add_u32_e32 v138, s43, v138
	v_and_b32_e32 v139, 3, v138
	v_lshlrev_b32_e32 v139, s13, v139
	v_bfe_u32 v140, v138, 2, 2
	v_add_u32_e32 v139, v139, v140
	v_lshl_add_u32 v139, v139, 7, v162
	v_ashrrev_i32_e32 v138, 4, v138
	v_med3_i32 v138, v138, 0, s14
	v_lshl_add_u32 v138, v138, 9, v139
	global_load_dwordx4 v[100:103], v138, s[22:23]
	s_add_i32 s2, s42, 16
	v_add_u32_e32 v138, s2, v164
	v_lshlrev_b32_e32 v138, 2, v138
	v_add_u32_e32 v138, s43, v138
	v_and_b32_e32 v139, 3, v138
	v_lshlrev_b32_e32 v139, s13, v139
	v_bfe_u32 v140, v138, 2, 2
	v_add_u32_e32 v139, v139, v140
	v_lshl_add_u32 v139, v139, 7, v162
	v_ashrrev_i32_e32 v138, 4, v138
	v_med3_i32 v138, v138, 0, s14
	v_lshl_add_u32 v138, v138, 9, v139
	global_load_dwordx4 v[104:107], v138, s[22:23]
	s_add_i32 s2, s42, 24
	v_add_u32_e32 v138, s2, v164
	v_lshlrev_b32_e32 v138, 2, v138
	v_add_u32_e32 v138, s43, v138
	v_and_b32_e32 v139, 3, v138
	v_lshlrev_b32_e32 v139, s13, v139
	v_bfe_u32 v140, v138, 2, 2
	v_add_u32_e32 v139, v139, v140
	v_lshl_add_u32 v139, v139, 7, v162
	v_ashrrev_i32_e32 v138, 4, v138
	v_med3_i32 v138, v138, 0, s14
	v_lshl_add_u32 v138, v138, 9, v139
	global_load_dwordx4 v[108:111], v138, s[22:23]
	v_mov_b32_e32 v132, 0
	v_mov_b32_e32 v133, 0
	ds_read_b128 v[204:207], v149
	ds_read_b128 v[208:211], v149 offset:64
	ds_read_b128 v[212:215], v149 offset:2304
	ds_read_b128 v[216:219], v149 offset:2368
	ds_read_b128 v[220:223], v149 offset:4608
	ds_read_b128 v[224:227], v149 offset:4672
	ds_read_b128 v[228:231], v149 offset:6912
	ds_read_b128 v[232:235], v149 offset:6976
	s_waitcnt lgkmcnt(0)
	v_mfma_f32_16x16x32_bf16 v[236:239], v[204:207], v[48:51], 0
	v_mfma_f32_16x16x32_bf16 v[236:239], v[208:211], v[52:55], v[236:239]
	v_mfma_f32_16x16x32_bf16 v[240:243], v[212:215], v[48:51], 0
	v_mfma_f32_16x16x32_bf16 v[240:243], v[216:219], v[52:55], v[240:243]
	v_mfma_f32_16x16x32_bf16 v[248:251], v[212:215], v[56:59], 0
	v_mfma_f32_16x16x32_bf16 v[248:251], v[216:219], v[60:63], v[248:251]
	s_nop 7
	v_min_f32_e32 v152, 0x42a00000, v236
	v_min_f32_e32 v153, 0x42a00000, v237
	v_min_f32_e32 v154, 0x42a00000, v238
	v_min_f32_e32 v155, 0x42a00000, v239
	v_mfma_f32_16x16x32_bf16 v[236:239], v[220:223], v[48:51], 0
	v_mfma_f32_16x16x32_bf16 v[236:239], v[224:227], v[52:55], v[236:239]
	v_mfma_f32_16x16x32_bf16 v[244:247], v[220:223], v[56:59], 0
	v_mfma_f32_16x16x32_bf16 v[244:247], v[224:227], v[60:63], v[244:247]
	ds_read_b128 v[204:207], v149 offset:9216
	ds_read_b128 v[208:211], v149 offset:9280
	v_mul_f32_e32 v152, 0x3fb8aa3b, v152
	v_mul_f32_e32 v153, 0x3fb8aa3b, v153
	v_mul_f32_e32 v154, 0x3fb8aa3b, v154
	v_mul_f32_e32 v155, 0x3fb8aa3b, v155
	v_exp_f32_e32 v152, v152
	v_exp_f32_e32 v153, v153
	v_exp_f32_e32 v154, v154
	v_exp_f32_e32 v155, v155
	v_add_u32_e32 v138, 0, v175
	v_add_u32_e32 v139, 1, v175
	v_add_u32_e32 v140, 2, v175
	v_add_u32_e32 v141, 3, v175
	v_cmp_gt_u32_e64 s[70:71], s44, v138
	v_cmp_gt_u32_e64 s[72:73], s44, v139
	v_cmp_gt_u32_e64 s[74:75], s44, v140
	v_cmp_gt_u32_e64 s[76:77], s44, v141
	v_cndmask_b32_e64 v152, 0, v152, s[54:55]
	v_cndmask_b32_e64 v153, 0, v153, s[56:57]
	v_cndmask_b32_e64 v154, 0, v154, s[58:59]
	v_cndmask_b32_e64 v155, 0, v155, s[60:61]
	v_cndmask_b32_e64 v152, 0, v152, s[70:71]
	v_cndmask_b32_e64 v153, 0, v153, s[72:73]
	v_cndmask_b32_e64 v154, 0, v154, s[74:75]
	v_cndmask_b32_e64 v155, 0, v155, s[76:77]
	v_add_f32_e32 v132, v132, v152
	v_add_f32_e32 v132, v132, v153
	v_add_f32_e32 v132, v132, v154
	v_add_f32_e32 v132, v132, v155
	v_cvt_pk_bf16_f32 v112, v152, v153
	v_cvt_pk_bf16_f32 v113, v154, v155
	v_min_f32_e32 v152, 0x42a00000, v240
	v_min_f32_e32 v153, 0x42a00000, v241
	v_min_f32_e32 v154, 0x42a00000, v242
	v_min_f32_e32 v155, 0x42a00000, v243
	v_min_f32_e32 v156, 0x42a00000, v248
	v_min_f32_e32 v157, 0x42a00000, v249
	v_min_f32_e32 v158, 0x42a00000, v250
	v_min_f32_e32 v159, 0x42a00000, v251
	v_mfma_f32_16x16x32_bf16 v[240:243], v[228:231], v[48:51], 0
	v_mfma_f32_16x16x32_bf16 v[240:243], v[232:235], v[52:55], v[240:243]
	v_mfma_f32_16x16x32_bf16 v[248:251], v[228:231], v[56:59], 0
	v_mfma_f32_16x16x32_bf16 v[248:251], v[232:235], v[60:63], v[248:251]
	ds_read_b128 v[212:215], v149 offset:11520
	ds_read_b128 v[216:219], v149 offset:11584
	v_mul_f32_e32 v152, 0x3fb8aa3b, v152
	v_mul_f32_e32 v153, 0x3fb8aa3b, v153
	v_mul_f32_e32 v154, 0x3fb8aa3b, v154
	v_mul_f32_e32 v155, 0x3fb8aa3b, v155
	v_exp_f32_e32 v152, v152
	v_exp_f32_e32 v153, v153
	v_exp_f32_e32 v154, v154
	v_exp_f32_e32 v155, v155
	v_add_u32_e32 v138, 16, v175
	v_add_u32_e32 v139, 17, v175
	v_add_u32_e32 v140, 18, v175
	v_add_u32_e32 v141, 19, v175
	v_cmp_gt_u32_e64 s[70:71], s44, v138
	v_cmp_gt_u32_e64 s[72:73], s44, v139
	v_cmp_gt_u32_e64 s[74:75], s44, v140
	v_cmp_gt_u32_e64 s[76:77], s44, v141
	v_cndmask_b32_e64 v152, 0, v152, s[70:71]
	v_cndmask_b32_e64 v153, 0, v153, s[72:73]
	v_cndmask_b32_e64 v154, 0, v154, s[74:75]
	v_cndmask_b32_e64 v155, 0, v155, s[76:77]
	v_add_f32_e32 v132, v132, v152
	v_add_f32_e32 v132, v132, v153
	v_add_f32_e32 v132, v132, v154
	v_add_f32_e32 v132, v132, v155
	v_cvt_pk_bf16_f32 v114, v152, v153
	v_cvt_pk_bf16_f32 v115, v154, v155
	v_mul_f32_e32 v156, 0x3fb8aa3b, v156
	v_mul_f32_e32 v157, 0x3fb8aa3b, v157
	v_mul_f32_e32 v158, 0x3fb8aa3b, v158
	v_mul_f32_e32 v159, 0x3fb8aa3b, v159
	v_exp_f32_e32 v156, v156
	v_exp_f32_e32 v157, v157
	v_exp_f32_e32 v158, v158
	v_exp_f32_e32 v159, v159
	v_add_u32_e32 v138, 16, v175
	v_add_u32_e32 v139, 17, v175
	v_add_u32_e32 v140, 18, v175
	v_add_u32_e32 v141, 19, v175
	v_cmp_gt_u32_e64 s[70:71], s44, v138
	v_cmp_gt_u32_e64 s[72:73], s44, v139
	v_cmp_gt_u32_e64 s[74:75], s44, v140
	v_cmp_gt_u32_e64 s[76:77], s44, v141
	v_cndmask_b32_e64 v156, 0, v156, s[54:55]
	v_cndmask_b32_e64 v157, 0, v157, s[56:57]
	v_cndmask_b32_e64 v158, 0, v158, s[58:59]
	v_cndmask_b32_e64 v159, 0, v159, s[60:61]
	v_cndmask_b32_e64 v156, 0, v156, s[70:71]
	v_cndmask_b32_e64 v157, 0, v157, s[72:73]
	v_cndmask_b32_e64 v158, 0, v158, s[74:75]
	v_cndmask_b32_e64 v159, 0, v159, s[76:77]
	v_add_f32_e32 v133, v133, v156
	v_add_f32_e32 v133, v133, v157
	v_add_f32_e32 v133, v133, v158
	v_add_f32_e32 v133, v133, v159
	v_cvt_pk_bf16_f32 v186, v156, v157
	v_cvt_pk_bf16_f32 v187, v158, v159
	v_min_f32_e32 v152, 0x42a00000, v236
	v_min_f32_e32 v153, 0x42a00000, v237
	v_min_f32_e32 v154, 0x42a00000, v238
	v_min_f32_e32 v155, 0x42a00000, v239
	v_min_f32_e32 v156, 0x42a00000, v244
	v_min_f32_e32 v157, 0x42a00000, v245
	v_min_f32_e32 v158, 0x42a00000, v246
	v_min_f32_e32 v159, 0x42a00000, v247
	s_waitcnt lgkmcnt(2)
	v_mfma_f32_16x16x32_bf16 v[236:239], v[204:207], v[48:51], 0
	v_mfma_f32_16x16x32_bf16 v[236:239], v[208:211], v[52:55], v[236:239]
	v_mfma_f32_16x16x32_bf16 v[244:247], v[204:207], v[56:59], 0
	v_mfma_f32_16x16x32_bf16 v[244:247], v[208:211], v[60:63], v[244:247]
	ds_read_b128 v[220:223], v149 offset:13824
	ds_read_b128 v[224:227], v149 offset:13888
	v_mul_f32_e32 v152, 0x3fb8aa3b, v152
	v_mul_f32_e32 v153, 0x3fb8aa3b, v153
	v_mul_f32_e32 v154, 0x3fb8aa3b, v154
	v_mul_f32_e32 v155, 0x3fb8aa3b, v155
	v_exp_f32_e32 v152, v152
	v_exp_f32_e32 v153, v153
	v_exp_f32_e32 v154, v154
	v_exp_f32_e32 v155, v155
	v_add_u32_e32 v138, 32, v175
	v_add_u32_e32 v139, 33, v175
	v_add_u32_e32 v140, 34, v175
	v_add_u32_e32 v141, 35, v175
	v_cmp_gt_u32_e64 s[70:71], s44, v138
	v_cmp_gt_u32_e64 s[72:73], s44, v139
	v_cmp_gt_u32_e64 s[74:75], s44, v140
	v_cmp_gt_u32_e64 s[76:77], s44, v141
	v_cndmask_b32_e64 v152, 0, v152, s[70:71]
	v_cndmask_b32_e64 v153, 0, v153, s[72:73]
	v_cndmask_b32_e64 v154, 0, v154, s[74:75]
	v_cndmask_b32_e64 v155, 0, v155, s[76:77]
	v_add_f32_e32 v132, v132, v152
	v_add_f32_e32 v132, v132, v153
	v_add_f32_e32 v132, v132, v154
	v_add_f32_e32 v132, v132, v155
	v_cvt_pk_bf16_f32 v116, v152, v153
	v_cvt_pk_bf16_f32 v117, v154, v155
	v_mul_f32_e32 v156, 0x3fb8aa3b, v156
	v_mul_f32_e32 v157, 0x3fb8aa3b, v157
	v_mul_f32_e32 v158, 0x3fb8aa3b, v158
	v_mul_f32_e32 v159, 0x3fb8aa3b, v159
	v_exp_f32_e32 v156, v156
	v_exp_f32_e32 v157, v157
	v_exp_f32_e32 v158, v158
	v_exp_f32_e32 v159, v159
	v_add_u32_e32 v138, 32, v175
	v_add_u32_e32 v139, 33, v175
	v_add_u32_e32 v140, 34, v175
	v_add_u32_e32 v141, 35, v175
	v_cmp_gt_u32_e64 s[70:71], s44, v138
	v_cmp_gt_u32_e64 s[72:73], s44, v139
	v_cmp_gt_u32_e64 s[74:75], s44, v140
	v_cmp_gt_u32_e64 s[76:77], s44, v141
	v_cndmask_b32_e64 v156, 0, v156, s[70:71]
	v_cndmask_b32_e64 v157, 0, v157, s[72:73]
	v_cndmask_b32_e64 v158, 0, v158, s[74:75]
	v_cndmask_b32_e64 v159, 0, v159, s[76:77]
	v_add_f32_e32 v133, v133, v156
	v_add_f32_e32 v133, v133, v157
	v_add_f32_e32 v133, v133, v158
	v_add_f32_e32 v133, v133, v159
	v_cvt_pk_bf16_f32 v188, v156, v157
	v_cvt_pk_bf16_f32 v189, v158, v159
	v_min_f32_e32 v152, 0x42a00000, v240
	v_min_f32_e32 v153, 0x42a00000, v241
	v_min_f32_e32 v154, 0x42a00000, v242
	v_min_f32_e32 v155, 0x42a00000, v243
	v_min_f32_e32 v156, 0x42a00000, v248
	v_min_f32_e32 v157, 0x42a00000, v249
	v_min_f32_e32 v158, 0x42a00000, v250
	v_min_f32_e32 v159, 0x42a00000, v251
	s_waitcnt lgkmcnt(2)
	v_mfma_f32_16x16x32_bf16 v[240:243], v[212:215], v[48:51], 0
	v_mfma_f32_16x16x32_bf16 v[240:243], v[216:219], v[52:55], v[240:243]
	v_mfma_f32_16x16x32_bf16 v[248:251], v[212:215], v[56:59], 0
	v_mfma_f32_16x16x32_bf16 v[248:251], v[216:219], v[60:63], v[248:251]
	ds_read_b128 v[228:231], v149 offset:16128
	ds_read_b128 v[232:235], v149 offset:16192
	v_mul_f32_e32 v152, 0x3fb8aa3b, v152
	v_mul_f32_e32 v153, 0x3fb8aa3b, v153
	v_mul_f32_e32 v154, 0x3fb8aa3b, v154
	v_mul_f32_e32 v155, 0x3fb8aa3b, v155
	v_exp_f32_e32 v152, v152
	v_exp_f32_e32 v153, v153
	v_exp_f32_e32 v154, v154
	v_exp_f32_e32 v155, v155
	v_add_u32_e32 v138, 48, v175
	v_add_u32_e32 v139, 49, v175
	v_add_u32_e32 v140, 50, v175
	v_add_u32_e32 v141, 51, v175
	v_cmp_gt_u32_e64 s[70:71], s44, v138
	v_cmp_gt_u32_e64 s[72:73], s44, v139
	v_cmp_gt_u32_e64 s[74:75], s44, v140
	v_cmp_gt_u32_e64 s[76:77], s44, v141
	v_cndmask_b32_e64 v152, 0, v152, s[70:71]
	v_cndmask_b32_e64 v153, 0, v153, s[72:73]
	v_cndmask_b32_e64 v154, 0, v154, s[74:75]
	v_cndmask_b32_e64 v155, 0, v155, s[76:77]
	v_add_f32_e32 v132, v132, v152
	v_add_f32_e32 v132, v132, v153
	v_add_f32_e32 v132, v132, v154
	v_add_f32_e32 v132, v132, v155
	v_cvt_pk_bf16_f32 v118, v152, v153
	v_cvt_pk_bf16_f32 v119, v154, v155
	v_mul_f32_e32 v156, 0x3fb8aa3b, v156
	v_mul_f32_e32 v157, 0x3fb8aa3b, v157
	v_mul_f32_e32 v158, 0x3fb8aa3b, v158
	v_mul_f32_e32 v159, 0x3fb8aa3b, v159
	v_exp_f32_e32 v156, v156
	v_exp_f32_e32 v157, v157
	v_exp_f32_e32 v158, v158
	v_exp_f32_e32 v159, v159
	v_add_u32_e32 v138, 48, v175
	v_add_u32_e32 v139, 49, v175
	v_add_u32_e32 v140, 50, v175
	v_add_u32_e32 v141, 51, v175
	v_cmp_gt_u32_e64 s[70:71], s44, v138
	v_cmp_gt_u32_e64 s[72:73], s44, v139
	v_cmp_gt_u32_e64 s[74:75], s44, v140
	v_cmp_gt_u32_e64 s[76:77], s44, v141
	v_cndmask_b32_e64 v156, 0, v156, s[70:71]
	v_cndmask_b32_e64 v157, 0, v157, s[72:73]
	v_cndmask_b32_e64 v158, 0, v158, s[74:75]
	v_cndmask_b32_e64 v159, 0, v159, s[76:77]
	v_add_f32_e32 v133, v133, v156
	v_add_f32_e32 v133, v133, v157
	v_add_f32_e32 v133, v133, v158
	v_add_f32_e32 v133, v133, v159
	v_cvt_pk_bf16_f32 v190, v156, v157
	v_cvt_pk_bf16_f32 v191, v158, v159
	v_min_f32_e32 v152, 0x42a00000, v236
	v_min_f32_e32 v153, 0x42a00000, v237
	v_min_f32_e32 v154, 0x42a00000, v238
	v_min_f32_e32 v155, 0x42a00000, v239
	v_min_f32_e32 v156, 0x42a00000, v244
	v_min_f32_e32 v157, 0x42a00000, v245
	v_min_f32_e32 v158, 0x42a00000, v246
	v_min_f32_e32 v159, 0x42a00000, v247
	s_waitcnt lgkmcnt(2)
	v_mfma_f32_16x16x32_bf16 v[236:239], v[220:223], v[48:51], 0
	v_mfma_f32_16x16x32_bf16 v[236:239], v[224:227], v[52:55], v[236:239]
	v_mfma_f32_16x16x32_bf16 v[244:247], v[220:223], v[56:59], 0
	v_mfma_f32_16x16x32_bf16 v[244:247], v[224:227], v[60:63], v[244:247]
	ds_read_b128 v[204:207], v149 offset:18432
	ds_read_b128 v[208:211], v149 offset:18496
	v_mul_f32_e32 v152, 0x3fb8aa3b, v152
	v_mul_f32_e32 v153, 0x3fb8aa3b, v153
	v_mul_f32_e32 v154, 0x3fb8aa3b, v154
	v_mul_f32_e32 v155, 0x3fb8aa3b, v155
	v_exp_f32_e32 v152, v152
	v_exp_f32_e32 v153, v153
	v_exp_f32_e32 v154, v154
	v_exp_f32_e32 v155, v155
	v_add_u32_e32 v138, 64, v175
	v_add_u32_e32 v139, 0x41, v175
	v_add_u32_e32 v140, 0x42, v175
	v_add_u32_e32 v141, 0x43, v175
	v_cmp_gt_u32_e64 s[70:71], s44, v138
	v_cmp_gt_u32_e64 s[72:73], s44, v139
	v_cmp_gt_u32_e64 s[74:75], s44, v140
	v_cmp_gt_u32_e64 s[76:77], s44, v141
	v_cndmask_b32_e64 v152, 0, v152, s[70:71]
	v_cndmask_b32_e64 v153, 0, v153, s[72:73]
	v_cndmask_b32_e64 v154, 0, v154, s[74:75]
	v_cndmask_b32_e64 v155, 0, v155, s[76:77]
	v_add_f32_e32 v132, v132, v152
	v_add_f32_e32 v132, v132, v153
	v_add_f32_e32 v132, v132, v154
	v_add_f32_e32 v132, v132, v155
	v_cvt_pk_bf16_f32 v120, v152, v153
	v_cvt_pk_bf16_f32 v121, v154, v155
	v_mul_f32_e32 v156, 0x3fb8aa3b, v156
	v_mul_f32_e32 v157, 0x3fb8aa3b, v157
	v_mul_f32_e32 v158, 0x3fb8aa3b, v158
	v_mul_f32_e32 v159, 0x3fb8aa3b, v159
	v_exp_f32_e32 v156, v156
	v_exp_f32_e32 v157, v157
	v_exp_f32_e32 v158, v158
	v_exp_f32_e32 v159, v159
	v_add_u32_e32 v138, 64, v175
	v_add_u32_e32 v139, 0x41, v175
	v_add_u32_e32 v140, 0x42, v175
	v_add_u32_e32 v141, 0x43, v175
	v_cmp_gt_u32_e64 s[70:71], s44, v138
	v_cmp_gt_u32_e64 s[72:73], s44, v139
	v_cmp_gt_u32_e64 s[74:75], s44, v140
	v_cmp_gt_u32_e64 s[76:77], s44, v141
	v_cndmask_b32_e64 v156, 0, v156, s[70:71]
	v_cndmask_b32_e64 v157, 0, v157, s[72:73]
	v_cndmask_b32_e64 v158, 0, v158, s[74:75]
	v_cndmask_b32_e64 v159, 0, v159, s[76:77]
	v_add_f32_e32 v133, v133, v156
	v_add_f32_e32 v133, v133, v157
	v_add_f32_e32 v133, v133, v158
	v_add_f32_e32 v133, v133, v159
	v_cvt_pk_bf16_f32 v192, v156, v157
	v_cvt_pk_bf16_f32 v193, v158, v159
	v_min_f32_e32 v152, 0x42a00000, v240
	v_min_f32_e32 v153, 0x42a00000, v241
	v_min_f32_e32 v154, 0x42a00000, v242
	v_min_f32_e32 v155, 0x42a00000, v243
	v_min_f32_e32 v156, 0x42a00000, v248
	v_min_f32_e32 v157, 0x42a00000, v249
	v_min_f32_e32 v158, 0x42a00000, v250
	v_min_f32_e32 v159, 0x42a00000, v251
	s_waitcnt lgkmcnt(2)
	v_mfma_f32_16x16x32_bf16 v[240:243], v[228:231], v[48:51], 0
	v_mfma_f32_16x16x32_bf16 v[240:243], v[232:235], v[52:55], v[240:243]
	v_mfma_f32_16x16x32_bf16 v[248:251], v[228:231], v[56:59], 0
	v_mfma_f32_16x16x32_bf16 v[248:251], v[232:235], v[60:63], v[248:251]
	ds_read_b128 v[212:215], v149 offset:20736
	ds_read_b128 v[216:219], v149 offset:20800
	v_mul_f32_e32 v152, 0x3fb8aa3b, v152
	v_mul_f32_e32 v153, 0x3fb8aa3b, v153
	v_mul_f32_e32 v154, 0x3fb8aa3b, v154
	v_mul_f32_e32 v155, 0x3fb8aa3b, v155
	v_exp_f32_e32 v152, v152
	v_exp_f32_e32 v153, v153
	v_exp_f32_e32 v154, v154
	v_exp_f32_e32 v155, v155
	v_add_u32_e32 v138, 0x50, v175
	v_add_u32_e32 v139, 0x51, v175
	v_add_u32_e32 v140, 0x52, v175
	v_add_u32_e32 v141, 0x53, v175
	v_cmp_gt_u32_e64 s[70:71], s44, v138
	v_cmp_gt_u32_e64 s[72:73], s44, v139
	v_cmp_gt_u32_e64 s[74:75], s44, v140
	v_cmp_gt_u32_e64 s[76:77], s44, v141
	v_cndmask_b32_e64 v152, 0, v152, s[70:71]
	v_cndmask_b32_e64 v153, 0, v153, s[72:73]
	v_cndmask_b32_e64 v154, 0, v154, s[74:75]
	v_cndmask_b32_e64 v155, 0, v155, s[76:77]
	v_add_f32_e32 v132, v132, v152
	v_add_f32_e32 v132, v132, v153
	v_add_f32_e32 v132, v132, v154
	v_add_f32_e32 v132, v132, v155
	v_cvt_pk_bf16_f32 v122, v152, v153
	v_cvt_pk_bf16_f32 v123, v154, v155
	v_mul_f32_e32 v156, 0x3fb8aa3b, v156
	v_mul_f32_e32 v157, 0x3fb8aa3b, v157
	v_mul_f32_e32 v158, 0x3fb8aa3b, v158
	v_mul_f32_e32 v159, 0x3fb8aa3b, v159
	v_exp_f32_e32 v156, v156
	v_exp_f32_e32 v157, v157
	v_exp_f32_e32 v158, v158
	v_exp_f32_e32 v159, v159
	v_add_u32_e32 v138, 0x50, v175
	v_add_u32_e32 v139, 0x51, v175
	v_add_u32_e32 v140, 0x52, v175
	v_add_u32_e32 v141, 0x53, v175
	v_cmp_gt_u32_e64 s[70:71], s44, v138
	v_cmp_gt_u32_e64 s[72:73], s44, v139
	v_cmp_gt_u32_e64 s[74:75], s44, v140
	v_cmp_gt_u32_e64 s[76:77], s44, v141
	v_cndmask_b32_e64 v156, 0, v156, s[70:71]
	v_cndmask_b32_e64 v157, 0, v157, s[72:73]
	v_cndmask_b32_e64 v158, 0, v158, s[74:75]
	v_cndmask_b32_e64 v159, 0, v159, s[76:77]
	v_add_f32_e32 v133, v133, v156
	v_add_f32_e32 v133, v133, v157
	v_add_f32_e32 v133, v133, v158
	v_add_f32_e32 v133, v133, v159
	v_cvt_pk_bf16_f32 v194, v156, v157
	v_cvt_pk_bf16_f32 v195, v158, v159
	v_min_f32_e32 v152, 0x42a00000, v236
	v_min_f32_e32 v153, 0x42a00000, v237
	v_min_f32_e32 v154, 0x42a00000, v238
	v_min_f32_e32 v155, 0x42a00000, v239
	v_min_f32_e32 v156, 0x42a00000, v244
	v_min_f32_e32 v157, 0x42a00000, v245
	v_min_f32_e32 v158, 0x42a00000, v246
	v_min_f32_e32 v159, 0x42a00000, v247
	s_waitcnt lgkmcnt(2)
	v_mfma_f32_16x16x32_bf16 v[236:239], v[204:207], v[48:51], 0
	v_mfma_f32_16x16x32_bf16 v[236:239], v[208:211], v[52:55], v[236:239]
	v_mfma_f32_16x16x32_bf16 v[244:247], v[204:207], v[56:59], 0
	v_mfma_f32_16x16x32_bf16 v[244:247], v[208:211], v[60:63], v[244:247]
	v_mul_f32_e32 v152, 0x3fb8aa3b, v152
	v_mul_f32_e32 v153, 0x3fb8aa3b, v153
	v_mul_f32_e32 v154, 0x3fb8aa3b, v154
	v_mul_f32_e32 v155, 0x3fb8aa3b, v155
	v_exp_f32_e32 v152, v152
	v_exp_f32_e32 v153, v153
	v_exp_f32_e32 v154, v154
	v_exp_f32_e32 v155, v155
	v_add_u32_e32 v138, 0x60, v175
	v_add_u32_e32 v139, 0x61, v175
	v_add_u32_e32 v140, 0x62, v175
	v_add_u32_e32 v141, 0x63, v175
	v_cmp_gt_u32_e64 s[70:71], s44, v138
	v_cmp_gt_u32_e64 s[72:73], s44, v139
	v_cmp_gt_u32_e64 s[74:75], s44, v140
	v_cmp_gt_u32_e64 s[76:77], s44, v141
	v_cndmask_b32_e64 v152, 0, v152, s[70:71]
	v_cndmask_b32_e64 v153, 0, v153, s[72:73]
	v_cndmask_b32_e64 v154, 0, v154, s[74:75]
	v_cndmask_b32_e64 v155, 0, v155, s[76:77]
	v_add_f32_e32 v132, v132, v152
	v_add_f32_e32 v132, v132, v153
	v_add_f32_e32 v132, v132, v154
	v_add_f32_e32 v132, v132, v155
	v_cvt_pk_bf16_f32 v124, v152, v153
	v_cvt_pk_bf16_f32 v125, v154, v155
	v_mul_f32_e32 v156, 0x3fb8aa3b, v156
	v_mul_f32_e32 v157, 0x3fb8aa3b, v157
	v_mul_f32_e32 v158, 0x3fb8aa3b, v158
	v_mul_f32_e32 v159, 0x3fb8aa3b, v159
	v_exp_f32_e32 v156, v156
	v_exp_f32_e32 v157, v157
	v_exp_f32_e32 v158, v158
	v_exp_f32_e32 v159, v159
	v_add_u32_e32 v138, 0x60, v175
	v_add_u32_e32 v139, 0x61, v175
	v_add_u32_e32 v140, 0x62, v175
	v_add_u32_e32 v141, 0x63, v175
	v_cmp_gt_u32_e64 s[70:71], s44, v138
	v_cmp_gt_u32_e64 s[72:73], s44, v139
	v_cmp_gt_u32_e64 s[74:75], s44, v140
	v_cmp_gt_u32_e64 s[76:77], s44, v141
	v_cndmask_b32_e64 v156, 0, v156, s[70:71]
	v_cndmask_b32_e64 v157, 0, v157, s[72:73]
	v_cndmask_b32_e64 v158, 0, v158, s[74:75]
	v_cndmask_b32_e64 v159, 0, v159, s[76:77]
	v_add_f32_e32 v133, v133, v156
	v_add_f32_e32 v133, v133, v157
	v_add_f32_e32 v133, v133, v158
	v_add_f32_e32 v133, v133, v159
	v_cvt_pk_bf16_f32 v196, v156, v157
	v_cvt_pk_bf16_f32 v197, v158, v159
	v_min_f32_e32 v152, 0x42a00000, v240
	v_min_f32_e32 v153, 0x42a00000, v241
	v_min_f32_e32 v154, 0x42a00000, v242
	v_min_f32_e32 v155, 0x42a00000, v243
	v_min_f32_e32 v156, 0x42a00000, v248
	v_min_f32_e32 v157, 0x42a00000, v249
	v_min_f32_e32 v158, 0x42a00000, v250
	v_min_f32_e32 v159, 0x42a00000, v251
	s_waitcnt lgkmcnt(0)
	v_mfma_f32_16x16x32_bf16 v[248:251], v[212:215], v[56:59], 0
	v_mfma_f32_16x16x32_bf16 v[248:251], v[216:219], v[60:63], v[248:251]
	v_mul_f32_e32 v152, 0x3fb8aa3b, v152
	v_mul_f32_e32 v153, 0x3fb8aa3b, v153
	v_mul_f32_e32 v154, 0x3fb8aa3b, v154
	v_mul_f32_e32 v155, 0x3fb8aa3b, v155
	v_exp_f32_e32 v152, v152
	v_exp_f32_e32 v153, v153
	v_exp_f32_e32 v154, v154
	v_exp_f32_e32 v155, v155
	v_add_u32_e32 v138, 0x70, v175
	v_add_u32_e32 v139, 0x71, v175
	v_add_u32_e32 v140, 0x72, v175
	v_add_u32_e32 v141, 0x73, v175
	v_cmp_gt_u32_e64 s[70:71], s44, v138
	v_cmp_gt_u32_e64 s[72:73], s44, v139
	v_cmp_gt_u32_e64 s[74:75], s44, v140
	v_cmp_gt_u32_e64 s[76:77], s44, v141
	v_cndmask_b32_e64 v152, 0, v152, s[70:71]
	v_cndmask_b32_e64 v153, 0, v153, s[72:73]
	v_cndmask_b32_e64 v154, 0, v154, s[74:75]
	v_cndmask_b32_e64 v155, 0, v155, s[76:77]
	v_add_f32_e32 v132, v132, v152
	v_add_f32_e32 v132, v132, v153
	v_add_f32_e32 v132, v132, v154
	v_add_f32_e32 v132, v132, v155
	v_cvt_pk_bf16_f32 v126, v152, v153
	v_cvt_pk_bf16_f32 v127, v154, v155
	v_mul_f32_e32 v156, 0x3fb8aa3b, v156
	v_mul_f32_e32 v157, 0x3fb8aa3b, v157
	v_mul_f32_e32 v158, 0x3fb8aa3b, v158
	v_mul_f32_e32 v159, 0x3fb8aa3b, v159
	v_exp_f32_e32 v156, v156
	v_exp_f32_e32 v157, v157
	v_exp_f32_e32 v158, v158
	v_exp_f32_e32 v159, v159
	v_add_u32_e32 v138, 0x70, v175
	v_add_u32_e32 v139, 0x71, v175
	v_add_u32_e32 v140, 0x72, v175
	v_add_u32_e32 v141, 0x73, v175
	v_cmp_gt_u32_e64 s[70:71], s44, v138
	v_cmp_gt_u32_e64 s[72:73], s44, v139
	v_cmp_gt_u32_e64 s[74:75], s44, v140
	v_cmp_gt_u32_e64 s[76:77], s44, v141
	v_cndmask_b32_e64 v156, 0, v156, s[70:71]
	v_cndmask_b32_e64 v157, 0, v157, s[72:73]
	v_cndmask_b32_e64 v158, 0, v158, s[74:75]
	v_cndmask_b32_e64 v159, 0, v159, s[76:77]
	v_add_f32_e32 v133, v133, v156
	v_add_f32_e32 v133, v133, v157
	v_add_f32_e32 v133, v133, v158
	v_add_f32_e32 v133, v133, v159
	v_cvt_pk_bf16_f32 v198, v156, v157
	v_cvt_pk_bf16_f32 v199, v158, v159
	v_min_f32_e32 v152, 0x42a00000, v236
	v_min_f32_e32 v153, 0x42a00000, v237
	v_min_f32_e32 v154, 0x42a00000, v238
	v_min_f32_e32 v155, 0x42a00000, v239
	v_min_f32_e32 v156, 0x42a00000, v244
	v_min_f32_e32 v157, 0x42a00000, v245
	v_min_f32_e32 v158, 0x42a00000, v246
	v_min_f32_e32 v159, 0x42a00000, v247
	v_mul_f32_e32 v152, 0x3fb8aa3b, v152
	v_mul_f32_e32 v153, 0x3fb8aa3b, v153
	v_mul_f32_e32 v154, 0x3fb8aa3b, v154
	v_mul_f32_e32 v155, 0x3fb8aa3b, v155
	v_exp_f32_e32 v152, v152
	v_exp_f32_e32 v153, v153
	v_exp_f32_e32 v154, v154
	v_exp_f32_e32 v155, v155
	v_add_u32_e32 v138, 0x80, v175
	v_add_u32_e32 v139, 0x81, v175
	v_add_u32_e32 v140, 0x82, v175
	v_add_u32_e32 v141, 0x83, v175
	v_cmp_gt_u32_e64 s[70:71], s44, v138
	v_cmp_gt_u32_e64 s[72:73], s44, v139
	v_cmp_gt_u32_e64 s[74:75], s44, v140
	v_cmp_gt_u32_e64 s[76:77], s44, v141
	v_cndmask_b32_e64 v152, 0, v152, s[62:63]
	v_cndmask_b32_e64 v153, 0, v153, s[64:65]
	v_cndmask_b32_e64 v154, 0, v154, s[66:67]
	v_cndmask_b32_e64 v155, 0, v155, s[68:69]
	v_cndmask_b32_e64 v152, 0, v152, s[70:71]
	v_cndmask_b32_e64 v153, 0, v153, s[72:73]
	v_cndmask_b32_e64 v154, 0, v154, s[74:75]
	v_cndmask_b32_e64 v155, 0, v155, s[76:77]
	v_add_f32_e32 v132, v132, v152
	v_add_f32_e32 v132, v132, v153
	v_add_f32_e32 v132, v132, v154
	v_add_f32_e32 v132, v132, v155
	v_cvt_pk_bf16_f32 v128, v152, v153
	v_cvt_pk_bf16_f32 v129, v154, v155
	v_mul_f32_e32 v156, 0x3fb8aa3b, v156
	v_mul_f32_e32 v157, 0x3fb8aa3b, v157
	v_mul_f32_e32 v158, 0x3fb8aa3b, v158
	v_mul_f32_e32 v159, 0x3fb8aa3b, v159
	v_exp_f32_e32 v156, v156
	v_exp_f32_e32 v157, v157
	v_exp_f32_e32 v158, v158
	v_exp_f32_e32 v159, v159
	v_add_u32_e32 v138, 0x80, v175
	v_add_u32_e32 v139, 0x81, v175
	v_add_u32_e32 v140, 0x82, v175
	v_add_u32_e32 v141, 0x83, v175
	v_cmp_gt_u32_e64 s[70:71], s44, v138
	v_cmp_gt_u32_e64 s[72:73], s44, v139
	v_cmp_gt_u32_e64 s[74:75], s44, v140
	v_cmp_gt_u32_e64 s[76:77], s44, v141
	v_cndmask_b32_e64 v156, 0, v156, s[70:71]
	v_cndmask_b32_e64 v157, 0, v157, s[72:73]
	v_cndmask_b32_e64 v158, 0, v158, s[74:75]
	v_cndmask_b32_e64 v159, 0, v159, s[76:77]
	v_add_f32_e32 v133, v133, v156
	v_add_f32_e32 v133, v133, v157
	v_add_f32_e32 v133, v133, v158
	v_add_f32_e32 v133, v133, v159
	v_cvt_pk_bf16_f32 v200, v156, v157
	v_cvt_pk_bf16_f32 v201, v158, v159
	v_min_f32_e32 v156, 0x42a00000, v248
	v_min_f32_e32 v157, 0x42a00000, v249
	v_min_f32_e32 v158, 0x42a00000, v250
	v_min_f32_e32 v159, 0x42a00000, v251
	v_mul_f32_e32 v156, 0x3fb8aa3b, v156
	v_mul_f32_e32 v157, 0x3fb8aa3b, v157
	v_mul_f32_e32 v158, 0x3fb8aa3b, v158
	v_mul_f32_e32 v159, 0x3fb8aa3b, v159
	v_exp_f32_e32 v156, v156
	v_exp_f32_e32 v157, v157
	v_exp_f32_e32 v158, v158
	v_exp_f32_e32 v159, v159
	v_add_u32_e32 v138, 0x90, v175
	v_add_u32_e32 v139, 0x91, v175
	v_add_u32_e32 v140, 0x92, v175
	v_add_u32_e32 v141, 0x93, v175
	v_cmp_gt_u32_e64 s[70:71], s44, v138
	v_cmp_gt_u32_e64 s[72:73], s44, v139
	v_cmp_gt_u32_e64 s[74:75], s44, v140
	v_cmp_gt_u32_e64 s[76:77], s44, v141
	v_cndmask_b32_e64 v156, 0, v156, s[62:63]
	v_cndmask_b32_e64 v157, 0, v157, s[64:65]
	v_cndmask_b32_e64 v158, 0, v158, s[66:67]
	v_cndmask_b32_e64 v159, 0, v159, s[68:69]
	v_cndmask_b32_e64 v156, 0, v156, s[70:71]
	v_cndmask_b32_e64 v157, 0, v157, s[72:73]
	v_cndmask_b32_e64 v158, 0, v158, s[74:75]
	v_cndmask_b32_e64 v159, 0, v159, s[76:77]
	v_add_f32_e32 v133, v133, v156
	v_add_f32_e32 v133, v133, v157
	v_add_f32_e32 v133, v133, v158
	v_add_f32_e32 v133, v133, v159
	v_cvt_pk_bf16_f32 v202, v156, v157
	v_cvt_pk_bf16_f32 v203, v158, v159
	global_load_dwordx4 v[48:51], v143, s[18:19]
	global_load_dwordx4 v[52:55], v143, s[18:19] offset:64
	global_load_dwordx4 v[56:59], v147, s[18:19]
	global_load_dwordx4 v[60:63], v147, s[18:19] offset:64
	ds_bpermute_b32 v142, v167, v132
	s_waitcnt lgkmcnt(0)
	v_add_f32_e32 v132, v132, v142
	ds_bpermute_b32 v142, v168, v132
	s_waitcnt lgkmcnt(0)
	v_add_f32_e32 v132, v132, v142
	ds_bpermute_b32 v142, v167, v133
	s_waitcnt lgkmcnt(0)
	v_add_f32_e32 v133, v133, v142
	ds_bpermute_b32 v142, v168, v133
	s_waitcnt lgkmcnt(0)
	v_add_f32_e32 v133, v133, v142
	ds_read_b64_tr_b16 v[236:237], v151 offset:0
	ds_read_b64_tr_b16 v[238:239], v151 offset:2304
	ds_read_b64_tr_b16 v[240:241], v151 offset:32
	ds_read_b64_tr_b16 v[242:243], v151 offset:2336
	ds_read_b64_tr_b16 v[244:245], v151 offset:64
	ds_read_b64_tr_b16 v[246:247], v151 offset:2368
	ds_read_b64_tr_b16 v[248:249], v151 offset:96
	ds_read_b64_tr_b16 v[250:251], v151 offset:2400
	s_waitcnt lgkmcnt(0)
	v_mfma_f32_16x16x32_bf16 v[204:207], v[236:239], v[112:115], 0
	v_mfma_f32_16x16x32_bf16 v[208:211], v[240:243], v[112:115], 0
	v_mfma_f32_16x16x32_bf16 v[212:215], v[244:247], v[112:115], 0
	v_mfma_f32_16x16x32_bf16 v[216:219], v[248:251], v[112:115], 0
	v_mfma_f32_16x16x32_bf16 v[220:223], v[236:239], v[184:187], 0
	v_mfma_f32_16x16x32_bf16 v[224:227], v[240:243], v[184:187], 0
	v_mfma_f32_16x16x32_bf16 v[228:231], v[244:247], v[184:187], 0
	v_mfma_f32_16x16x32_bf16 v[232:235], v[248:251], v[184:187], 0
	s_nop 7
	ds_read_b64_tr_b16 v[236:237], v151 offset:4608
	ds_read_b64_tr_b16 v[238:239], v151 offset:6912
	ds_read_b64_tr_b16 v[240:241], v151 offset:4640
	ds_read_b64_tr_b16 v[242:243], v151 offset:6944
	ds_read_b64_tr_b16 v[244:245], v151 offset:4672
	ds_read_b64_tr_b16 v[246:247], v151 offset:6976
	ds_read_b64_tr_b16 v[248:249], v151 offset:4704
	ds_read_b64_tr_b16 v[250:251], v151 offset:7008
	s_waitcnt lgkmcnt(0)
	v_mfma_f32_16x16x32_bf16 v[204:207], v[236:239], v[116:119], v[204:207]
	v_mfma_f32_16x16x32_bf16 v[208:211], v[240:243], v[116:119], v[208:211]
	v_mfma_f32_16x16x32_bf16 v[212:215], v[244:247], v[116:119], v[212:215]
	v_mfma_f32_16x16x32_bf16 v[216:219], v[248:251], v[116:119], v[216:219]
	v_mfma_f32_16x16x32_bf16 v[220:223], v[236:239], v[188:191], v[220:223]
	v_mfma_f32_16x16x32_bf16 v[224:227], v[240:243], v[188:191], v[224:227]
	v_mfma_f32_16x16x32_bf16 v[228:231], v[244:247], v[188:191], v[228:231]
	v_mfma_f32_16x16x32_bf16 v[232:235], v[248:251], v[188:191], v[232:235]
	s_nop 7
	ds_read_b64_tr_b16 v[236:237], v151 offset:9216
	ds_read_b64_tr_b16 v[238:239], v151 offset:11520
	ds_read_b64_tr_b16 v[240:241], v151 offset:9248
	ds_read_b64_tr_b16 v[242:243], v151 offset:11552
	ds_read_b64_tr_b16 v[244:245], v151 offset:9280
	ds_read_b64_tr_b16 v[246:247], v151 offset:11584
	ds_read_b64_tr_b16 v[248:249], v151 offset:9312
	ds_read_b64_tr_b16 v[250:251], v151 offset:11616
	s_waitcnt lgkmcnt(0)
	v_mfma_f32_16x16x32_bf16 v[204:207], v[236:239], v[120:123], v[204:207]
	v_mfma_f32_16x16x32_bf16 v[208:211], v[240:243], v[120:123], v[208:211]
	v_mfma_f32_16x16x32_bf16 v[212:215], v[244:247], v[120:123], v[212:215]
	v_mfma_f32_16x16x32_bf16 v[216:219], v[248:251], v[120:123], v[216:219]
	v_mfma_f32_16x16x32_bf16 v[220:223], v[236:239], v[192:195], v[220:223]
	v_mfma_f32_16x16x32_bf16 v[224:227], v[240:243], v[192:195], v[224:227]
	v_mfma_f32_16x16x32_bf16 v[228:231], v[244:247], v[192:195], v[228:231]
	v_mfma_f32_16x16x32_bf16 v[232:235], v[248:251], v[192:195], v[232:235]
	s_nop 7
	ds_read_b64_tr_b16 v[236:237], v151 offset:13824
	ds_read_b64_tr_b16 v[238:239], v151 offset:16128
	ds_read_b64_tr_b16 v[240:241], v151 offset:13856
	ds_read_b64_tr_b16 v[242:243], v151 offset:16160
	ds_read_b64_tr_b16 v[244:245], v151 offset:13888
	ds_read_b64_tr_b16 v[246:247], v151 offset:16192
	ds_read_b64_tr_b16 v[248:249], v151 offset:13920
	ds_read_b64_tr_b16 v[250:251], v151 offset:16224
	s_waitcnt lgkmcnt(0)
	v_mfma_f32_16x16x32_bf16 v[204:207], v[236:239], v[124:127], v[204:207]
	v_mfma_f32_16x16x32_bf16 v[208:211], v[240:243], v[124:127], v[208:211]
	v_mfma_f32_16x16x32_bf16 v[212:215], v[244:247], v[124:127], v[212:215]
	v_mfma_f32_16x16x32_bf16 v[216:219], v[248:251], v[124:127], v[216:219]
	v_mfma_f32_16x16x32_bf16 v[220:223], v[236:239], v[196:199], v[220:223]
	v_mfma_f32_16x16x32_bf16 v[224:227], v[240:243], v[196:199], v[224:227]
	v_mfma_f32_16x16x32_bf16 v[228:231], v[244:247], v[196:199], v[228:231]
	v_mfma_f32_16x16x32_bf16 v[232:235], v[248:251], v[196:199], v[232:235]
	s_nop 7
	ds_read_b64_tr_b16 v[236:237], v151 offset:18432
	ds_read_b64_tr_b16 v[238:239], v151 offset:20736
	ds_read_b64_tr_b16 v[240:241], v151 offset:18464
	ds_read_b64_tr_b16 v[242:243], v151 offset:20768
	ds_read_b64_tr_b16 v[244:245], v151 offset:18496
	ds_read_b64_tr_b16 v[246:247], v151 offset:20800
	ds_read_b64_tr_b16 v[248:249], v151 offset:18528
	ds_read_b64_tr_b16 v[250:251], v151 offset:20832
	s_waitcnt lgkmcnt(0)
	v_mfma_f32_16x16x32_bf16 v[204:207], v[236:239], v[128:131], v[204:207]
	v_mfma_f32_16x16x32_bf16 v[208:211], v[240:243], v[128:131], v[208:211]
	v_mfma_f32_16x16x32_bf16 v[212:215], v[244:247], v[128:131], v[212:215]
	v_mfma_f32_16x16x32_bf16 v[216:219], v[248:251], v[128:131], v[216:219]
	v_mfma_f32_16x16x32_bf16 v[220:223], v[236:239], v[200:203], v[220:223]
	v_mfma_f32_16x16x32_bf16 v[224:227], v[240:243], v[200:203], v[224:227]
	v_mfma_f32_16x16x32_bf16 v[228:231], v[244:247], v[200:203], v[228:231]
	v_mfma_f32_16x16x32_bf16 v[232:235], v[248:251], v[200:203], v[232:235]
	s_barrier
	ds_write_b128 v173, v[204:207] offset:0
	ds_write_b128 v173, v[208:211] offset:64
	ds_write_b128 v173, v[212:215] offset:128
	ds_write_b128 v173, v[216:219] offset:192
	ds_write_b32 v174, v132 offset:0
	ds_write_b128 v173, v[220:223] offset:4624
	ds_write_b128 v173, v[224:227] offset:4688
	ds_write_b128 v173, v[228:231] offset:4752
	ds_write_b128 v173, v[232:235] offset:4816
	ds_write_b32 v174, v133 offset:64
	s_waitcnt lgkmcnt(0)
	s_barrier
	s_mov_b32 s40, s42
	s_mov_b32 s41, s43
	v_mov_b32_e32 v173, v176
	v_mov_b32_e32 v174, v177
	v_mov_b32_e32 v175, v178
	v_mov_b32_e32 v179, v183
	v_mov_b32_e32 v182, v252
	s_lshr_b32 s44, s33, 2
	s_lshr_b32 s42, s15, 4
	s_add_i32 s43, s0, 0
	s_waitcnt vmcnt(0)
	v_mov_b32_e32 v132, 0
	v_mov_b32_e32 v133, 0
	v_mfma_f32_16x16x32_bf16 v[236:239], v[0:3], v[48:51], 0
	v_mfma_f32_16x16x32_bf16 v[236:239], v[4:7], v[52:55], v[236:239]
	v_mfma_f32_16x16x32_bf16 v[240:243], v[8:11], v[48:51], 0
	v_mfma_f32_16x16x32_bf16 v[240:243], v[12:15], v[52:55], v[240:243]
	v_mfma_f32_16x16x32_bf16 v[248:251], v[8:11], v[56:59], 0
	v_mfma_f32_16x16x32_bf16 v[248:251], v[12:15], v[60:63], v[248:251]
	s_nop 7
	v_min_f32_e32 v152, 0x42a00000, v236
	v_min_f32_e32 v153, 0x42a00000, v237
	v_min_f32_e32 v154, 0x42a00000, v238
	v_min_f32_e32 v155, 0x42a00000, v239
	v_mfma_f32_16x16x32_bf16 v[236:239], v[16:19], v[48:51], 0
	v_mfma_f32_16x16x32_bf16 v[236:239], v[20:23], v[52:55], v[236:239]
	v_mfma_f32_16x16x32_bf16 v[244:247], v[16:19], v[56:59], 0
	v_mfma_f32_16x16x32_bf16 v[244:247], v[20:23], v[60:63], v[244:247]
	v_add_u32_e32 v136, 24, v182
	v_med3_i32 v136, v136, 0, s38
	v_lshl_add_u32 v136, v136, 9, v179
	global_load_dwordx4 v[0:3], v136, s[24:25]
	global_load_dwordx4 v[4:7], v136, s[24:25] offset:64
	v_mul_f32_e32 v152, 0x3fb8aa3b, v152
	v_mul_f32_e32 v153, 0x3fb8aa3b, v153
	v_mul_f32_e32 v154, 0x3fb8aa3b, v154
	v_mul_f32_e32 v155, 0x3fb8aa3b, v155
	v_exp_f32_e32 v152, v152
	v_exp_f32_e32 v153, v153
	v_exp_f32_e32 v154, v154
	v_exp_f32_e32 v155, v155
	v_add_u32_e32 v138, 0, v175
	v_add_u32_e32 v139, 1, v175
	v_add_u32_e32 v140, 2, v175
	v_add_u32_e32 v141, 3, v175
	v_cmp_gt_u32_e64 s[70:71], s44, v138
	v_cmp_gt_u32_e64 s[72:73], s44, v139
	v_cmp_gt_u32_e64 s[74:75], s44, v140
	v_cmp_gt_u32_e64 s[76:77], s44, v141
	v_cndmask_b32_e64 v152, 0, v152, s[54:55]
	v_cndmask_b32_e64 v153, 0, v153, s[56:57]
	v_cndmask_b32_e64 v154, 0, v154, s[58:59]
	v_cndmask_b32_e64 v155, 0, v155, s[60:61]
	v_cndmask_b32_e64 v152, 0, v152, s[70:71]
	v_cndmask_b32_e64 v153, 0, v153, s[72:73]
	v_cndmask_b32_e64 v154, 0, v154, s[74:75]
	v_cndmask_b32_e64 v155, 0, v155, s[76:77]
	v_add_f32_e32 v132, v132, v152
	v_add_f32_e32 v132, v132, v153
	v_add_f32_e32 v132, v132, v154
	v_add_f32_e32 v132, v132, v155
	v_cvt_pk_bf16_f32 v112, v152, v153
	v_cvt_pk_bf16_f32 v113, v154, v155
	v_min_f32_e32 v152, 0x42a00000, v240
	v_min_f32_e32 v153, 0x42a00000, v241
	v_min_f32_e32 v154, 0x42a00000, v242
	v_min_f32_e32 v155, 0x42a00000, v243
	v_min_f32_e32 v156, 0x42a00000, v248
	v_min_f32_e32 v157, 0x42a00000, v249
	v_min_f32_e32 v158, 0x42a00000, v250
	v_min_f32_e32 v159, 0x42a00000, v251
	v_mfma_f32_16x16x32_bf16 v[240:243], v[24:27], v[48:51], 0
	v_mfma_f32_16x16x32_bf16 v[240:243], v[28:31], v[52:55], v[240:243]
	v_mfma_f32_16x16x32_bf16 v[248:251], v[24:27], v[56:59], 0
	v_mfma_f32_16x16x32_bf16 v[248:251], v[28:31], v[60:63], v[248:251]
	v_add_u32_e32 v135, 28, v182
	v_med3_i32 v135, v135, 0, s38
	v_lshl_add_u32 v135, v135, 9, v179
	global_load_dwordx4 v[8:11], v135, s[24:25]
	global_load_dwordx4 v[12:15], v135, s[24:25] offset:64
	v_mul_f32_e32 v152, 0x3fb8aa3b, v152
	v_mul_f32_e32 v153, 0x3fb8aa3b, v153
	v_mul_f32_e32 v154, 0x3fb8aa3b, v154
	v_mul_f32_e32 v155, 0x3fb8aa3b, v155
	v_exp_f32_e32 v152, v152
	v_exp_f32_e32 v153, v153
	v_exp_f32_e32 v154, v154
	v_exp_f32_e32 v155, v155
	v_add_u32_e32 v138, 16, v175
	v_add_u32_e32 v139, 17, v175
	v_add_u32_e32 v140, 18, v175
	v_add_u32_e32 v141, 19, v175
	v_cmp_gt_u32_e64 s[70:71], s44, v138
	v_cmp_gt_u32_e64 s[72:73], s44, v139
	v_cmp_gt_u32_e64 s[74:75], s44, v140
	v_cmp_gt_u32_e64 s[76:77], s44, v141
	v_cndmask_b32_e64 v152, 0, v152, s[70:71]
	v_cndmask_b32_e64 v153, 0, v153, s[72:73]
	v_cndmask_b32_e64 v154, 0, v154, s[74:75]
	v_cndmask_b32_e64 v155, 0, v155, s[76:77]
	v_add_f32_e32 v132, v132, v152
	v_add_f32_e32 v132, v132, v153
	v_add_f32_e32 v132, v132, v154
	v_add_f32_e32 v132, v132, v155
	v_cvt_pk_bf16_f32 v114, v152, v153
	v_cvt_pk_bf16_f32 v115, v154, v155
	v_mul_f32_e32 v156, 0x3fb8aa3b, v156
	v_mul_f32_e32 v157, 0x3fb8aa3b, v157
	v_mul_f32_e32 v158, 0x3fb8aa3b, v158
	v_mul_f32_e32 v159, 0x3fb8aa3b, v159
	v_exp_f32_e32 v156, v156
	v_exp_f32_e32 v157, v157
	v_exp_f32_e32 v158, v158
	v_exp_f32_e32 v159, v159
	v_add_u32_e32 v138, 16, v175
	v_add_u32_e32 v139, 17, v175
	v_add_u32_e32 v140, 18, v175
	v_add_u32_e32 v141, 19, v175
	v_cmp_gt_u32_e64 s[70:71], s44, v138
	v_cmp_gt_u32_e64 s[72:73], s44, v139
	v_cmp_gt_u32_e64 s[74:75], s44, v140
	v_cmp_gt_u32_e64 s[76:77], s44, v141
	v_cndmask_b32_e64 v156, 0, v156, s[54:55]
	v_cndmask_b32_e64 v157, 0, v157, s[56:57]
	v_cndmask_b32_e64 v158, 0, v158, s[58:59]
	v_cndmask_b32_e64 v159, 0, v159, s[60:61]
	v_cndmask_b32_e64 v156, 0, v156, s[70:71]
	v_cndmask_b32_e64 v157, 0, v157, s[72:73]
	v_cndmask_b32_e64 v158, 0, v158, s[74:75]
	v_cndmask_b32_e64 v159, 0, v159, s[76:77]
	v_add_f32_e32 v133, v133, v156
	v_add_f32_e32 v133, v133, v157
	v_add_f32_e32 v133, v133, v158
	v_add_f32_e32 v133, v133, v159
	v_cvt_pk_bf16_f32 v186, v156, v157
	v_cvt_pk_bf16_f32 v187, v158, v159
	v_min_f32_e32 v152, 0x42a00000, v236
	v_min_f32_e32 v153, 0x42a00000, v237
	v_min_f32_e32 v154, 0x42a00000, v238
	v_min_f32_e32 v155, 0x42a00000, v239
	v_min_f32_e32 v156, 0x42a00000, v244
	v_min_f32_e32 v157, 0x42a00000, v245
	v_min_f32_e32 v158, 0x42a00000, v246
	v_min_f32_e32 v159, 0x42a00000, v247
	v_mfma_f32_16x16x32_bf16 v[236:239], v[32:35], v[48:51], 0
	v_mfma_f32_16x16x32_bf16 v[236:239], v[36:39], v[52:55], v[236:239]
	v_mfma_f32_16x16x32_bf16 v[244:247], v[32:35], v[56:59], 0
	v_mfma_f32_16x16x32_bf16 v[244:247], v[36:39], v[60:63], v[244:247]
	v_add_u32_e32 v136, 32, v182
	v_med3_i32 v136, v136, 0, s38
	v_lshl_add_u32 v136, v136, 9, v179
	global_load_dwordx4 v[16:19], v136, s[24:25]
	global_load_dwordx4 v[20:23], v136, s[24:25] offset:64
	v_mul_f32_e32 v152, 0x3fb8aa3b, v152
	v_mul_f32_e32 v153, 0x3fb8aa3b, v153
	v_mul_f32_e32 v154, 0x3fb8aa3b, v154
	v_mul_f32_e32 v155, 0x3fb8aa3b, v155
	v_exp_f32_e32 v152, v152
	v_exp_f32_e32 v153, v153
	v_exp_f32_e32 v154, v154
	v_exp_f32_e32 v155, v155
	v_add_u32_e32 v138, 32, v175
	v_add_u32_e32 v139, 33, v175
	v_add_u32_e32 v140, 34, v175
	v_add_u32_e32 v141, 35, v175
	v_cmp_gt_u32_e64 s[70:71], s44, v138
	v_cmp_gt_u32_e64 s[72:73], s44, v139
	v_cmp_gt_u32_e64 s[74:75], s44, v140
	v_cmp_gt_u32_e64 s[76:77], s44, v141
	v_cndmask_b32_e64 v152, 0, v152, s[70:71]
	v_cndmask_b32_e64 v153, 0, v153, s[72:73]
	v_cndmask_b32_e64 v154, 0, v154, s[74:75]
	v_cndmask_b32_e64 v155, 0, v155, s[76:77]
	v_add_f32_e32 v132, v132, v152
	v_add_f32_e32 v132, v132, v153
	v_add_f32_e32 v132, v132, v154
	v_add_f32_e32 v132, v132, v155
	v_cvt_pk_bf16_f32 v116, v152, v153
	v_cvt_pk_bf16_f32 v117, v154, v155
	v_mul_f32_e32 v156, 0x3fb8aa3b, v156
	v_mul_f32_e32 v157, 0x3fb8aa3b, v157
	v_mul_f32_e32 v158, 0x3fb8aa3b, v158
	v_mul_f32_e32 v159, 0x3fb8aa3b, v159
	v_exp_f32_e32 v156, v156
	v_exp_f32_e32 v157, v157
	v_exp_f32_e32 v158, v158
	v_exp_f32_e32 v159, v159
	v_add_u32_e32 v138, 32, v175
	v_add_u32_e32 v139, 33, v175
	v_add_u32_e32 v140, 34, v175
	v_add_u32_e32 v141, 35, v175
	v_cmp_gt_u32_e64 s[70:71], s44, v138
	v_cmp_gt_u32_e64 s[72:73], s44, v139
	v_cmp_gt_u32_e64 s[74:75], s44, v140
	v_cmp_gt_u32_e64 s[76:77], s44, v141
	v_cndmask_b32_e64 v156, 0, v156, s[70:71]
	v_cndmask_b32_e64 v157, 0, v157, s[72:73]
	v_cndmask_b32_e64 v158, 0, v158, s[74:75]
	v_cndmask_b32_e64 v159, 0, v159, s[76:77]
	v_add_f32_e32 v133, v133, v156
	v_add_f32_e32 v133, v133, v157
	v_add_f32_e32 v133, v133, v158
	v_add_f32_e32 v133, v133, v159
	v_cvt_pk_bf16_f32 v188, v156, v157
	v_cvt_pk_bf16_f32 v189, v158, v159
	v_min_f32_e32 v152, 0x42a00000, v240
	v_min_f32_e32 v153, 0x42a00000, v241
	v_min_f32_e32 v154, 0x42a00000, v242
	v_min_f32_e32 v155, 0x42a00000, v243
	v_min_f32_e32 v156, 0x42a00000, v248
	v_min_f32_e32 v157, 0x42a00000, v249
	v_min_f32_e32 v158, 0x42a00000, v250
	v_min_f32_e32 v159, 0x42a00000, v251
	v_mfma_f32_16x16x32_bf16 v[240:243], v[40:43], v[48:51], 0
	v_mfma_f32_16x16x32_bf16 v[240:243], v[44:47], v[52:55], v[240:243]
	v_mfma_f32_16x16x32_bf16 v[248:251], v[40:43], v[56:59], 0
	v_mfma_f32_16x16x32_bf16 v[248:251], v[44:47], v[60:63], v[248:251]
	v_add_u32_e32 v135, 36, v182
	v_med3_i32 v135, v135, 0, s38
	v_lshl_add_u32 v135, v135, 9, v179
	global_load_dwordx4 v[24:27], v135, s[24:25]
	global_load_dwordx4 v[28:31], v135, s[24:25] offset:64
	v_mul_f32_e32 v152, 0x3fb8aa3b, v152
	v_mul_f32_e32 v153, 0x3fb8aa3b, v153
	v_mul_f32_e32 v154, 0x3fb8aa3b, v154
	v_mul_f32_e32 v155, 0x3fb8aa3b, v155
	v_exp_f32_e32 v152, v152
	v_exp_f32_e32 v153, v153
	v_exp_f32_e32 v154, v154
	v_exp_f32_e32 v155, v155
	v_add_u32_e32 v138, 48, v175
	v_add_u32_e32 v139, 49, v175
	v_add_u32_e32 v140, 50, v175
	v_add_u32_e32 v141, 51, v175
	v_cmp_gt_u32_e64 s[70:71], s44, v138
	v_cmp_gt_u32_e64 s[72:73], s44, v139
	v_cmp_gt_u32_e64 s[74:75], s44, v140
	v_cmp_gt_u32_e64 s[76:77], s44, v141
	v_cndmask_b32_e64 v152, 0, v152, s[70:71]
	v_cndmask_b32_e64 v153, 0, v153, s[72:73]
	v_cndmask_b32_e64 v154, 0, v154, s[74:75]
	v_cndmask_b32_e64 v155, 0, v155, s[76:77]
	v_add_f32_e32 v132, v132, v152
	v_add_f32_e32 v132, v132, v153
	v_add_f32_e32 v132, v132, v154
	v_add_f32_e32 v132, v132, v155
	v_cvt_pk_bf16_f32 v118, v152, v153
	v_cvt_pk_bf16_f32 v119, v154, v155
	v_mul_f32_e32 v156, 0x3fb8aa3b, v156
	v_mul_f32_e32 v157, 0x3fb8aa3b, v157
	v_mul_f32_e32 v158, 0x3fb8aa3b, v158
	v_mul_f32_e32 v159, 0x3fb8aa3b, v159
	v_exp_f32_e32 v156, v156
	v_exp_f32_e32 v157, v157
	v_exp_f32_e32 v158, v158
	v_exp_f32_e32 v159, v159
	v_add_u32_e32 v138, 48, v175
	v_add_u32_e32 v139, 49, v175
	v_add_u32_e32 v140, 50, v175
	v_add_u32_e32 v141, 51, v175
	v_cmp_gt_u32_e64 s[70:71], s44, v138
	v_cmp_gt_u32_e64 s[72:73], s44, v139
	v_cmp_gt_u32_e64 s[74:75], s44, v140
	v_cmp_gt_u32_e64 s[76:77], s44, v141
	v_cndmask_b32_e64 v156, 0, v156, s[70:71]
	v_cndmask_b32_e64 v157, 0, v157, s[72:73]
	v_cndmask_b32_e64 v158, 0, v158, s[74:75]
	v_cndmask_b32_e64 v159, 0, v159, s[76:77]
	v_add_f32_e32 v133, v133, v156
	v_add_f32_e32 v133, v133, v157
	v_add_f32_e32 v133, v133, v158
	v_add_f32_e32 v133, v133, v159
	v_cvt_pk_bf16_f32 v190, v156, v157
	v_cvt_pk_bf16_f32 v191, v158, v159
	v_min_f32_e32 v152, 0x42a00000, v236
	v_min_f32_e32 v153, 0x42a00000, v237
	v_min_f32_e32 v154, 0x42a00000, v238
	v_min_f32_e32 v155, 0x42a00000, v239
	v_min_f32_e32 v156, 0x42a00000, v244
	v_min_f32_e32 v157, 0x42a00000, v245
	v_min_f32_e32 v158, 0x42a00000, v246
	v_min_f32_e32 v159, 0x42a00000, v247
	s_waitcnt vmcnt(6)
	v_mfma_f32_16x16x32_bf16 v[236:239], v[0:3], v[48:51], 0
	v_mfma_f32_16x16x32_bf16 v[236:239], v[4:7], v[52:55], v[236:239]
	v_mfma_f32_16x16x32_bf16 v[244:247], v[0:3], v[56:59], 0
	v_mfma_f32_16x16x32_bf16 v[244:247], v[4:7], v[60:63], v[244:247]
	v_mul_f32_e32 v152, 0x3fb8aa3b, v152
	v_mul_f32_e32 v153, 0x3fb8aa3b, v153
	v_mul_f32_e32 v154, 0x3fb8aa3b, v154
	v_mul_f32_e32 v155, 0x3fb8aa3b, v155
	v_exp_f32_e32 v152, v152
	v_exp_f32_e32 v153, v153
	v_exp_f32_e32 v154, v154
	v_exp_f32_e32 v155, v155
	v_add_u32_e32 v138, 64, v175
	v_add_u32_e32 v139, 0x41, v175
	v_add_u32_e32 v140, 0x42, v175
	v_add_u32_e32 v141, 0x43, v175
	v_cmp_gt_u32_e64 s[70:71], s44, v138
	v_cmp_gt_u32_e64 s[72:73], s44, v139
	v_cmp_gt_u32_e64 s[74:75], s44, v140
	v_cmp_gt_u32_e64 s[76:77], s44, v141
	v_cndmask_b32_e64 v152, 0, v152, s[70:71]
	v_cndmask_b32_e64 v153, 0, v153, s[72:73]
	v_cndmask_b32_e64 v154, 0, v154, s[74:75]
	v_cndmask_b32_e64 v155, 0, v155, s[76:77]
	v_add_f32_e32 v132, v132, v152
	v_add_f32_e32 v132, v132, v153
	v_add_f32_e32 v132, v132, v154
	v_add_f32_e32 v132, v132, v155
	v_cvt_pk_bf16_f32 v120, v152, v153
	v_cvt_pk_bf16_f32 v121, v154, v155
	v_mul_f32_e32 v156, 0x3fb8aa3b, v156
	v_mul_f32_e32 v157, 0x3fb8aa3b, v157
	v_mul_f32_e32 v158, 0x3fb8aa3b, v158
	v_mul_f32_e32 v159, 0x3fb8aa3b, v159
	v_exp_f32_e32 v156, v156
	v_exp_f32_e32 v157, v157
	v_exp_f32_e32 v158, v158
	v_exp_f32_e32 v159, v159
	v_add_u32_e32 v138, 64, v175
	v_add_u32_e32 v139, 0x41, v175
	v_add_u32_e32 v140, 0x42, v175
	v_add_u32_e32 v141, 0x43, v175
	v_cmp_gt_u32_e64 s[70:71], s44, v138
	v_cmp_gt_u32_e64 s[72:73], s44, v139
	v_cmp_gt_u32_e64 s[74:75], s44, v140
	v_cmp_gt_u32_e64 s[76:77], s44, v141
	v_cndmask_b32_e64 v156, 0, v156, s[70:71]
	v_cndmask_b32_e64 v157, 0, v157, s[72:73]
	v_cndmask_b32_e64 v158, 0, v158, s[74:75]
	v_cndmask_b32_e64 v159, 0, v159, s[76:77]
	v_add_f32_e32 v133, v133, v156
	v_add_f32_e32 v133, v133, v157
	v_add_f32_e32 v133, v133, v158
	v_add_f32_e32 v133, v133, v159
	v_cvt_pk_bf16_f32 v192, v156, v157
	v_cvt_pk_bf16_f32 v193, v158, v159
	v_min_f32_e32 v152, 0x42a00000, v240
	v_min_f32_e32 v153, 0x42a00000, v241
	v_min_f32_e32 v154, 0x42a00000, v242
	v_min_f32_e32 v155, 0x42a00000, v243
	v_min_f32_e32 v156, 0x42a00000, v248
	v_min_f32_e32 v157, 0x42a00000, v249
	v_min_f32_e32 v158, 0x42a00000, v250
	v_min_f32_e32 v159, 0x42a00000, v251
	s_waitcnt vmcnt(4)
	v_mfma_f32_16x16x32_bf16 v[240:243], v[8:11], v[48:51], 0
	v_mfma_f32_16x16x32_bf16 v[240:243], v[12:15], v[52:55], v[240:243]
	v_mfma_f32_16x16x32_bf16 v[248:251], v[8:11], v[56:59], 0
	v_mfma_f32_16x16x32_bf16 v[248:251], v[12:15], v[60:63], v[248:251]
	v_mul_f32_e32 v152, 0x3fb8aa3b, v152
	v_mul_f32_e32 v153, 0x3fb8aa3b, v153
	v_mul_f32_e32 v154, 0x3fb8aa3b, v154
	v_mul_f32_e32 v155, 0x3fb8aa3b, v155
	v_exp_f32_e32 v152, v152
	v_exp_f32_e32 v153, v153
	v_exp_f32_e32 v154, v154
	v_exp_f32_e32 v155, v155
	v_add_u32_e32 v138, 0x50, v175
	v_add_u32_e32 v139, 0x51, v175
	v_add_u32_e32 v140, 0x52, v175
	v_add_u32_e32 v141, 0x53, v175
	v_cmp_gt_u32_e64 s[70:71], s44, v138
	v_cmp_gt_u32_e64 s[72:73], s44, v139
	v_cmp_gt_u32_e64 s[74:75], s44, v140
	v_cmp_gt_u32_e64 s[76:77], s44, v141
	v_cndmask_b32_e64 v152, 0, v152, s[70:71]
	v_cndmask_b32_e64 v153, 0, v153, s[72:73]
	v_cndmask_b32_e64 v154, 0, v154, s[74:75]
	v_cndmask_b32_e64 v155, 0, v155, s[76:77]
	v_add_f32_e32 v132, v132, v152
	v_add_f32_e32 v132, v132, v153
	v_add_f32_e32 v132, v132, v154
	v_add_f32_e32 v132, v132, v155
	v_cvt_pk_bf16_f32 v122, v152, v153
	v_cvt_pk_bf16_f32 v123, v154, v155
	v_mul_f32_e32 v156, 0x3fb8aa3b, v156
	v_mul_f32_e32 v157, 0x3fb8aa3b, v157
	v_mul_f32_e32 v158, 0x3fb8aa3b, v158
	v_mul_f32_e32 v159, 0x3fb8aa3b, v159
	v_exp_f32_e32 v156, v156
	v_exp_f32_e32 v157, v157
	v_exp_f32_e32 v158, v158
	v_exp_f32_e32 v159, v159
	v_add_u32_e32 v138, 0x50, v175
	v_add_u32_e32 v139, 0x51, v175
	v_add_u32_e32 v140, 0x52, v175
	v_add_u32_e32 v141, 0x53, v175
	v_cmp_gt_u32_e64 s[70:71], s44, v138
	v_cmp_gt_u32_e64 s[72:73], s44, v139
	v_cmp_gt_u32_e64 s[74:75], s44, v140
	v_cmp_gt_u32_e64 s[76:77], s44, v141
	v_cndmask_b32_e64 v156, 0, v156, s[70:71]
	v_cndmask_b32_e64 v157, 0, v157, s[72:73]
	v_cndmask_b32_e64 v158, 0, v158, s[74:75]
	v_cndmask_b32_e64 v159, 0, v159, s[76:77]
	v_add_f32_e32 v133, v133, v156
	v_add_f32_e32 v133, v133, v157
	v_add_f32_e32 v133, v133, v158
	v_add_f32_e32 v133, v133, v159
	v_cvt_pk_bf16_f32 v194, v156, v157
	v_cvt_pk_bf16_f32 v195, v158, v159
	v_min_f32_e32 v152, 0x42a00000, v236
	v_min_f32_e32 v153, 0x42a00000, v237
	v_min_f32_e32 v154, 0x42a00000, v238
	v_min_f32_e32 v155, 0x42a00000, v239
	v_min_f32_e32 v156, 0x42a00000, v244
	v_min_f32_e32 v157, 0x42a00000, v245
	v_min_f32_e32 v158, 0x42a00000, v246
	v_min_f32_e32 v159, 0x42a00000, v247
	s_waitcnt vmcnt(2)
	v_mfma_f32_16x16x32_bf16 v[236:239], v[16:19], v[48:51], 0
	v_mfma_f32_16x16x32_bf16 v[236:239], v[20:23], v[52:55], v[236:239]
	v_mfma_f32_16x16x32_bf16 v[244:247], v[16:19], v[56:59], 0
	v_mfma_f32_16x16x32_bf16 v[244:247], v[20:23], v[60:63], v[244:247]
	v_mul_f32_e32 v152, 0x3fb8aa3b, v152
	v_mul_f32_e32 v153, 0x3fb8aa3b, v153
	v_mul_f32_e32 v154, 0x3fb8aa3b, v154
	v_mul_f32_e32 v155, 0x3fb8aa3b, v155
	v_exp_f32_e32 v152, v152
	v_exp_f32_e32 v153, v153
	v_exp_f32_e32 v154, v154
	v_exp_f32_e32 v155, v155
	v_add_u32_e32 v138, 0x60, v175
	v_add_u32_e32 v139, 0x61, v175
	v_add_u32_e32 v140, 0x62, v175
	v_add_u32_e32 v141, 0x63, v175
	v_cmp_gt_u32_e64 s[70:71], s44, v138
	v_cmp_gt_u32_e64 s[72:73], s44, v139
	v_cmp_gt_u32_e64 s[74:75], s44, v140
	v_cmp_gt_u32_e64 s[76:77], s44, v141
	v_cndmask_b32_e64 v152, 0, v152, s[70:71]
	v_cndmask_b32_e64 v153, 0, v153, s[72:73]
	v_cndmask_b32_e64 v154, 0, v154, s[74:75]
	v_cndmask_b32_e64 v155, 0, v155, s[76:77]
	v_add_f32_e32 v132, v132, v152
	v_add_f32_e32 v132, v132, v153
	v_add_f32_e32 v132, v132, v154
	v_add_f32_e32 v132, v132, v155
	v_cvt_pk_bf16_f32 v124, v152, v153
	v_cvt_pk_bf16_f32 v125, v154, v155
	v_mul_f32_e32 v156, 0x3fb8aa3b, v156
	v_mul_f32_e32 v157, 0x3fb8aa3b, v157
	v_mul_f32_e32 v158, 0x3fb8aa3b, v158
	v_mul_f32_e32 v159, 0x3fb8aa3b, v159
	v_exp_f32_e32 v156, v156
	v_exp_f32_e32 v157, v157
	v_exp_f32_e32 v158, v158
	v_exp_f32_e32 v159, v159
	v_add_u32_e32 v138, 0x60, v175
	v_add_u32_e32 v139, 0x61, v175
	v_add_u32_e32 v140, 0x62, v175
	v_add_u32_e32 v141, 0x63, v175
	v_cmp_gt_u32_e64 s[70:71], s44, v138
	v_cmp_gt_u32_e64 s[72:73], s44, v139
	v_cmp_gt_u32_e64 s[74:75], s44, v140
	v_cmp_gt_u32_e64 s[76:77], s44, v141
	v_cndmask_b32_e64 v156, 0, v156, s[70:71]
	v_cndmask_b32_e64 v157, 0, v157, s[72:73]
	v_cndmask_b32_e64 v158, 0, v158, s[74:75]
	v_cndmask_b32_e64 v159, 0, v159, s[76:77]
	v_add_f32_e32 v133, v133, v156
	v_add_f32_e32 v133, v133, v157
	v_add_f32_e32 v133, v133, v158
	v_add_f32_e32 v133, v133, v159
	v_cvt_pk_bf16_f32 v196, v156, v157
	v_cvt_pk_bf16_f32 v197, v158, v159
	v_min_f32_e32 v152, 0x42a00000, v240
	v_min_f32_e32 v153, 0x42a00000, v241
	v_min_f32_e32 v154, 0x42a00000, v242
	v_min_f32_e32 v155, 0x42a00000, v243
	v_min_f32_e32 v156, 0x42a00000, v248
	v_min_f32_e32 v157, 0x42a00000, v249
	v_min_f32_e32 v158, 0x42a00000, v250
	v_min_f32_e32 v159, 0x42a00000, v251
	s_waitcnt vmcnt(0)
	v_mfma_f32_16x16x32_bf16 v[248:251], v[24:27], v[56:59], 0
	v_mfma_f32_16x16x32_bf16 v[248:251], v[28:31], v[60:63], v[248:251]
	v_mul_f32_e32 v152, 0x3fb8aa3b, v152
	v_mul_f32_e32 v153, 0x3fb8aa3b, v153
	v_mul_f32_e32 v154, 0x3fb8aa3b, v154
	v_mul_f32_e32 v155, 0x3fb8aa3b, v155
	v_exp_f32_e32 v152, v152
	v_exp_f32_e32 v153, v153
	v_exp_f32_e32 v154, v154
	v_exp_f32_e32 v155, v155
	v_add_u32_e32 v138, 0x70, v175
	v_add_u32_e32 v139, 0x71, v175
	v_add_u32_e32 v140, 0x72, v175
	v_add_u32_e32 v141, 0x73, v175
	v_cmp_gt_u32_e64 s[70:71], s44, v138
	v_cmp_gt_u32_e64 s[72:73], s44, v139
	v_cmp_gt_u32_e64 s[74:75], s44, v140
	v_cmp_gt_u32_e64 s[76:77], s44, v141
	v_cndmask_b32_e64 v152, 0, v152, s[70:71]
	v_cndmask_b32_e64 v153, 0, v153, s[72:73]
	v_cndmask_b32_e64 v154, 0, v154, s[74:75]
	v_cndmask_b32_e64 v155, 0, v155, s[76:77]
	v_add_f32_e32 v132, v132, v152
	v_add_f32_e32 v132, v132, v153
	v_add_f32_e32 v132, v132, v154
	v_add_f32_e32 v132, v132, v155
	v_cvt_pk_bf16_f32 v126, v152, v153
	v_cvt_pk_bf16_f32 v127, v154, v155
	v_mul_f32_e32 v156, 0x3fb8aa3b, v156
	v_mul_f32_e32 v157, 0x3fb8aa3b, v157
	v_mul_f32_e32 v158, 0x3fb8aa3b, v158
	v_mul_f32_e32 v159, 0x3fb8aa3b, v159
	v_exp_f32_e32 v156, v156
	v_exp_f32_e32 v157, v157
	v_exp_f32_e32 v158, v158
	v_exp_f32_e32 v159, v159
	v_add_u32_e32 v138, 0x70, v175
	v_add_u32_e32 v139, 0x71, v175
	v_add_u32_e32 v140, 0x72, v175
	v_add_u32_e32 v141, 0x73, v175
	v_cmp_gt_u32_e64 s[70:71], s44, v138
	v_cmp_gt_u32_e64 s[72:73], s44, v139
	v_cmp_gt_u32_e64 s[74:75], s44, v140
	v_cmp_gt_u32_e64 s[76:77], s44, v141
	v_cndmask_b32_e64 v156, 0, v156, s[70:71]
	v_cndmask_b32_e64 v157, 0, v157, s[72:73]
	v_cndmask_b32_e64 v158, 0, v158, s[74:75]
	v_cndmask_b32_e64 v159, 0, v159, s[76:77]
	v_add_f32_e32 v133, v133, v156
	v_add_f32_e32 v133, v133, v157
	v_add_f32_e32 v133, v133, v158
	v_add_f32_e32 v133, v133, v159
	v_cvt_pk_bf16_f32 v198, v156, v157
	v_cvt_pk_bf16_f32 v199, v158, v159
	v_min_f32_e32 v152, 0x42a00000, v236
	v_min_f32_e32 v153, 0x42a00000, v237
	v_min_f32_e32 v154, 0x42a00000, v238
	v_min_f32_e32 v155, 0x42a00000, v239
	v_min_f32_e32 v156, 0x42a00000, v244
	v_min_f32_e32 v157, 0x42a00000, v245
	v_min_f32_e32 v158, 0x42a00000, v246
	v_min_f32_e32 v159, 0x42a00000, v247
	v_mul_f32_e32 v152, 0x3fb8aa3b, v152
	v_mul_f32_e32 v153, 0x3fb8aa3b, v153
	v_mul_f32_e32 v154, 0x3fb8aa3b, v154
	v_mul_f32_e32 v155, 0x3fb8aa3b, v155
	v_exp_f32_e32 v152, v152
	v_exp_f32_e32 v153, v153
	v_exp_f32_e32 v154, v154
	v_exp_f32_e32 v155, v155
	v_add_u32_e32 v138, 0x80, v175
	v_add_u32_e32 v139, 0x81, v175
	v_add_u32_e32 v140, 0x82, v175
	v_add_u32_e32 v141, 0x83, v175
	v_cmp_gt_u32_e64 s[70:71], s44, v138
	v_cmp_gt_u32_e64 s[72:73], s44, v139
	v_cmp_gt_u32_e64 s[74:75], s44, v140
	v_cmp_gt_u32_e64 s[76:77], s44, v141
	v_cndmask_b32_e64 v152, 0, v152, s[62:63]
	v_cndmask_b32_e64 v153, 0, v153, s[64:65]
	v_cndmask_b32_e64 v154, 0, v154, s[66:67]
	v_cndmask_b32_e64 v155, 0, v155, s[68:69]
	v_cndmask_b32_e64 v152, 0, v152, s[70:71]
	v_cndmask_b32_e64 v153, 0, v153, s[72:73]
	v_cndmask_b32_e64 v154, 0, v154, s[74:75]
	v_cndmask_b32_e64 v155, 0, v155, s[76:77]
	v_add_f32_e32 v132, v132, v152
	v_add_f32_e32 v132, v132, v153
	v_add_f32_e32 v132, v132, v154
	v_add_f32_e32 v132, v132, v155
	v_cvt_pk_bf16_f32 v128, v152, v153
	v_cvt_pk_bf16_f32 v129, v154, v155
	v_mul_f32_e32 v156, 0x3fb8aa3b, v156
	v_mul_f32_e32 v157, 0x3fb8aa3b, v157
	v_mul_f32_e32 v158, 0x3fb8aa3b, v158
	v_mul_f32_e32 v159, 0x3fb8aa3b, v159
	v_exp_f32_e32 v156, v156
	v_exp_f32_e32 v157, v157
	v_exp_f32_e32 v158, v158
	v_exp_f32_e32 v159, v159
	v_add_u32_e32 v138, 0x80, v175
	v_add_u32_e32 v139, 0x81, v175
	v_add_u32_e32 v140, 0x82, v175
	v_add_u32_e32 v141, 0x83, v175
	v_cmp_gt_u32_e64 s[70:71], s44, v138
	v_cmp_gt_u32_e64 s[72:73], s44, v139
	v_cmp_gt_u32_e64 s[74:75], s44, v140
	v_cmp_gt_u32_e64 s[76:77], s44, v141
	v_cndmask_b32_e64 v156, 0, v156, s[70:71]
	v_cndmask_b32_e64 v157, 0, v157, s[72:73]
	v_cndmask_b32_e64 v158, 0, v158, s[74:75]
	v_cndmask_b32_e64 v159, 0, v159, s[76:77]
	v_add_f32_e32 v133, v133, v156
	v_add_f32_e32 v133, v133, v157
	v_add_f32_e32 v133, v133, v158
	v_add_f32_e32 v133, v133, v159
	v_cvt_pk_bf16_f32 v200, v156, v157
	v_cvt_pk_bf16_f32 v201, v158, v159
	v_min_f32_e32 v156, 0x42a00000, v248
	v_min_f32_e32 v157, 0x42a00000, v249
	v_min_f32_e32 v158, 0x42a00000, v250
	v_min_f32_e32 v159, 0x42a00000, v251
	v_mul_f32_e32 v156, 0x3fb8aa3b, v156
	v_mul_f32_e32 v157, 0x3fb8aa3b, v157
	v_mul_f32_e32 v158, 0x3fb8aa3b, v158
	v_mul_f32_e32 v159, 0x3fb8aa3b, v159
	v_exp_f32_e32 v156, v156
	v_exp_f32_e32 v157, v157
	v_exp_f32_e32 v158, v158
	v_exp_f32_e32 v159, v159
	v_add_u32_e32 v138, 0x90, v175
	v_add_u32_e32 v139, 0x91, v175
	v_add_u32_e32 v140, 0x92, v175
	v_add_u32_e32 v141, 0x93, v175
	v_cmp_gt_u32_e64 s[70:71], s44, v138
	v_cmp_gt_u32_e64 s[72:73], s44, v139
	v_cmp_gt_u32_e64 s[74:75], s44, v140
	v_cmp_gt_u32_e64 s[76:77], s44, v141
	v_cndmask_b32_e64 v156, 0, v156, s[62:63]
	v_cndmask_b32_e64 v157, 0, v157, s[64:65]
	v_cndmask_b32_e64 v158, 0, v158, s[66:67]
	v_cndmask_b32_e64 v159, 0, v159, s[68:69]
	v_cndmask_b32_e64 v156, 0, v156, s[70:71]
	v_cndmask_b32_e64 v157, 0, v157, s[72:73]
	v_cndmask_b32_e64 v158, 0, v158, s[74:75]
	v_cndmask_b32_e64 v159, 0, v159, s[76:77]
	v_add_f32_e32 v133, v133, v156
	v_add_f32_e32 v133, v133, v157
	v_add_f32_e32 v133, v133, v158
	v_add_f32_e32 v133, v133, v159
	v_cvt_pk_bf16_f32 v202, v156, v157
	v_cvt_pk_bf16_f32 v203, v158, v159
	v_add_u32_e32 v134, s42, v160
	v_lshlrev_b32_e32 v134, 4, v134
	v_add_u32_e32 v134, s43, v134
	v_subrev_u32_e32 v135, s15, v134
	v_lshrrev_b32_e32 v136, 4, v135
	v_add_u32_e32 v136, v136, v135
	v_mad_u32_u24 v176, v136, s79, v161
	v_lshl_add_u32 v177, v135, 2, s80
	s_sub_i32 s2, s42, 64
	v_add_u32_e32 v178, s2, v169
	v_and_b32_e32 v135, 3, v134
	v_lshlrev_b32_e32 v135, s13, v135
	v_lshrrev_b32_e32 v136, 2, v134
	v_add_u32_e32 v135, v135, v136
	v_lshl_add_u32 v135, v135, 7, v161
	global_load_dwordx4 v[48:51], v135, s[18:19]
	global_load_dwordx4 v[52:55], v135, s[18:19] offset:64
	v_subrev_u32_e32 v134, 0x400, v134
	v_and_b32_e32 v137, 3, v134
	v_lshlrev_b32_e32 v137, s13, v137
	v_bfe_u32 v135, v134, 2, 2
	v_add_u32_e32 v137, v137, v135
	v_lshl_add_u32 v183, v137, 7, v161
	v_ashrrev_i32_e32 v252, 4, v134
	v_med3_i32 v136, v252, 0, s14
	v_lshl_add_u32 v136, v136, 9, v183
	global_load_dwordx4 v[0:3], v136, s[20:21]
	global_load_dwordx4 v[4:7], v136, s[20:21] offset:64
	v_add_u32_e32 v135, 16, v252
	v_med3_i32 v135, v135, 0, s14
	v_lshl_add_u32 v135, v135, 9, v183
	global_load_dwordx4 v[8:11], v135, s[20:21]
	global_load_dwordx4 v[12:15], v135, s[20:21] offset:64
	v_add_u32_e32 v136, 32, v252
	v_med3_i32 v136, v136, 0, s14
	v_lshl_add_u32 v136, v136, 9, v183
	global_load_dwordx4 v[16:19], v136, s[20:21]
	global_load_dwordx4 v[20:23], v136, s[20:21] offset:64
	v_add_u32_e32 v135, 48, v252
	v_med3_i32 v135, v135, 0, s14
	v_lshl_add_u32 v135, v135, 9, v183
	global_load_dwordx4 v[24:27], v135, s[20:21]
	global_load_dwordx4 v[28:31], v135, s[20:21] offset:64
	v_add_u32_e32 v136, 64, v252
	v_med3_i32 v136, v136, 0, s14
	v_lshl_add_u32 v136, v136, 9, v183
	global_load_dwordx4 v[32:35], v136, s[20:21]
	global_load_dwordx4 v[36:39], v136, s[20:21] offset:64
	v_add_u32_e32 v135, 0x50, v252
	v_med3_i32 v135, v135, 0, s14
	v_lshl_add_u32 v135, v135, 9, v183
	global_load_dwordx4 v[40:43], v135, s[20:21]
	global_load_dwordx4 v[44:47], v135, s[20:21] offset:64
	ds_bpermute_b32 v142, v167, v132
	s_waitcnt lgkmcnt(0)
	v_add_f32_e32 v132, v132, v142
	ds_bpermute_b32 v142, v168, v132
	s_waitcnt lgkmcnt(0)
	v_add_f32_e32 v132, v132, v142
	ds_bpermute_b32 v142, v167, v133
	s_waitcnt lgkmcnt(0)
	v_add_f32_e32 v133, v133, v142
	ds_bpermute_b32 v142, v168, v133
	s_waitcnt lgkmcnt(0)
	v_add_f32_e32 v133, v133, v142
	s_waitcnt vmcnt(14)
	ds_write_b128 v165, v[64:67]
	ds_write_b128 v165, v[68:71] offset:1152
	ds_write_b128 v165, v[72:75] offset:2304
	ds_write_b128 v165, v[76:79] offset:3456
	s_waitcnt lgkmcnt(0)
	ds_read_b64_tr_b16 v[236:237], v166
	ds_read_b64_tr_b16 v[238:239], v166 offset:2304
	ds_read_b64_tr_b16 v[240:241], v166 offset:32
	ds_read_b64_tr_b16 v[242:243], v166 offset:2336
	ds_read_b64_tr_b16 v[244:245], v166 offset:64
	ds_read_b64_tr_b16 v[246:247], v166 offset:2368
	ds_read_b64_tr_b16 v[248:249], v166 offset:96
	ds_read_b64_tr_b16 v[250:251], v166 offset:2400
	s_waitcnt lgkmcnt(0)
	s_add_i32 s2, s40, 32
	v_add_u32_e32 v138, s2, v164
	v_lshlrev_b32_e32 v138, 2, v138
	v_add_u32_e32 v138, s41, v138
	v_and_b32_e32 v139, 3, v138
	v_lshlrev_b32_e32 v139, s39, v139
	v_bfe_u32 v140, v138, 2, 2
	v_add_u32_e32 v139, v139, v140
	v_lshl_add_u32 v139, v139, 7, v162
	v_ashrrev_i32_e32 v138, 4, v138
	v_med3_i32 v138, v138, 0, s38
	v_lshl_add_u32 v138, v138, 9, v139
	global_load_dwordx4 v[64:67], v138, s[26:27]
	s_add_i32 s2, s40, 40
	v_add_u32_e32 v138, s2, v164
	v_lshlrev_b32_e32 v138, 2, v138
	v_add_u32_e32 v138, s41, v138
	v_and_b32_e32 v139, 3, v138
	v_lshlrev_b32_e32 v139, s39, v139
	v_bfe_u32 v140, v138, 2, 2
	v_add_u32_e32 v139, v139, v140
	v_lshl_add_u32 v139, v139, 7, v162
	v_ashrrev_i32_e32 v138, 4, v138
	v_med3_i32 v138, v138, 0, s38
	v_lshl_add_u32 v138, v138, 9, v139
	global_load_dwordx4 v[68:71], v138, s[26:27]
	s_add_i32 s2, s40, 48
	v_add_u32_e32 v138, s2, v164
	v_lshlrev_b32_e32 v138, 2, v138
	v_add_u32_e32 v138, s41, v138
	v_and_b32_e32 v139, 3, v138
	v_lshlrev_b32_e32 v139, s39, v139
	v_bfe_u32 v140, v138, 2, 2
	v_add_u32_e32 v139, v139, v140
	v_lshl_add_u32 v139, v139, 7, v162
	v_ashrrev_i32_e32 v138, 4, v138
	v_med3_i32 v138, v138, 0, s38
	v_lshl_add_u32 v138, v138, 9, v139
	global_load_dwordx4 v[72:75], v138, s[26:27]
	s_add_i32 s2, s40, 56
	v_add_u32_e32 v138, s2, v164
	v_lshlrev_b32_e32 v138, 2, v138
	v_add_u32_e32 v138, s41, v138
	v_and_b32_e32 v139, 3, v138
	v_lshlrev_b32_e32 v139, s39, v139
	v_bfe_u32 v140, v138, 2, 2
	v_add_u32_e32 v139, v139, v140
	v_lshl_add_u32 v139, v139, 7, v162
	v_ashrrev_i32_e32 v138, 4, v138
	v_med3_i32 v138, v138, 0, s38
	v_lshl_add_u32 v138, v138, 9, v139
	global_load_dwordx4 v[76:79], v138, s[26:27]
	ds_write_b128 v165, v[80:83]
	ds_write_b128 v165, v[84:87] offset:1152
	ds_write_b128 v165, v[88:91] offset:2304
	ds_write_b128 v165, v[92:95] offset:3456
	v_mfma_f32_16x16x32_bf16 v[204:207], v[236:239], v[112:115], 0
	v_mfma_f32_16x16x32_bf16 v[208:211], v[240:243], v[112:115], 0
	v_mfma_f32_16x16x32_bf16 v[212:215], v[244:247], v[112:115], 0
	v_mfma_f32_16x16x32_bf16 v[216:219], v[248:251], v[112:115], 0
	v_mfma_f32_16x16x32_bf16 v[220:223], v[236:239], v[184:187], 0
	v_mfma_f32_16x16x32_bf16 v[224:227], v[240:243], v[184:187], 0
	v_mfma_f32_16x16x32_bf16 v[228:231], v[244:247], v[184:187], 0
	v_mfma_f32_16x16x32_bf16 v[232:235], v[248:251], v[184:187], 0
	s_waitcnt lgkmcnt(0)
	ds_read_b64_tr_b16 v[236:237], v166
	ds_read_b64_tr_b16 v[238:239], v166 offset:2304
	ds_read_b64_tr_b16 v[240:241], v166 offset:32
	ds_read_b64_tr_b16 v[242:243], v166 offset:2336
	ds_read_b64_tr_b16 v[244:245], v166 offset:64
	ds_read_b64_tr_b16 v[246:247], v166 offset:2368
	ds_read_b64_tr_b16 v[248:249], v166 offset:96
	ds_read_b64_tr_b16 v[250:251], v166 offset:2400
	s_waitcnt lgkmcnt(0)
	s_add_i32 s2, s40, 64
	v_add_u32_e32 v138, s2, v164
	v_lshlrev_b32_e32 v138, 2, v138
	v_add_u32_e32 v138, s41, v138
	v_and_b32_e32 v139, 3, v138
	v_lshlrev_b32_e32 v139, s39, v139
	v_bfe_u32 v140, v138, 2, 2
	v_add_u32_e32 v139, v139, v140
	v_lshl_add_u32 v139, v139, 7, v162
	v_ashrrev_i32_e32 v138, 4, v138
	v_med3_i32 v138, v138, 0, s38
	v_lshl_add_u32 v138, v138, 9, v139
	global_load_dwordx4 v[80:83], v138, s[26:27]
	s_add_i32 s2, s40, 72
	v_add_u32_e32 v138, s2, v164
	v_lshlrev_b32_e32 v138, 2, v138
	v_add_u32_e32 v138, s41, v138
	v_and_b32_e32 v139, 3, v138
	v_lshlrev_b32_e32 v139, s39, v139
	v_bfe_u32 v140, v138, 2, 2
	v_add_u32_e32 v139, v139, v140
	v_lshl_add_u32 v139, v139, 7, v162
	v_ashrrev_i32_e32 v138, 4, v138
	v_med3_i32 v138, v138, 0, s38
	v_lshl_add_u32 v138, v138, 9, v139
	global_load_dwordx4 v[84:87], v138, s[26:27]
	s_add_i32 s2, s40, 80
	v_add_u32_e32 v138, s2, v164
	v_lshlrev_b32_e32 v138, 2, v138
	v_add_u32_e32 v138, s41, v138
	v_and_b32_e32 v139, 3, v138
	v_lshlrev_b32_e32 v139, s39, v139
	v_bfe_u32 v140, v138, 2, 2
	v_add_u32_e32 v139, v139, v140
	v_lshl_add_u32 v139, v139, 7, v162
	v_ashrrev_i32_e32 v138, 4, v138
	v_med3_i32 v138, v138, 0, s38
	v_lshl_add_u32 v138, v138, 9, v139
	global_load_dwordx4 v[88:91], v138, s[26:27]
	s_add_i32 s2, s40, 88
	v_add_u32_e32 v138, s2, v164
	v_lshlrev_b32_e32 v138, 2, v138
	v_add_u32_e32 v138, s41, v138
	v_and_b32_e32 v139, 3, v138
	v_lshlrev_b32_e32 v139, s39, v139
	v_bfe_u32 v140, v138, 2, 2
	v_add_u32_e32 v139, v139, v140
	v_lshl_add_u32 v139, v139, 7, v162
	v_ashrrev_i32_e32 v138, 4, v138
	v_med3_i32 v138, v138, 0, s38
	v_lshl_add_u32 v138, v138, 9, v139
	global_load_dwordx4 v[92:95], v138, s[26:27]
	ds_write_b128 v165, v[96:99]
	ds_write_b128 v165, v[100:103] offset:1152
	ds_write_b128 v165, v[104:107] offset:2304
	ds_write_b128 v165, v[108:111] offset:3456
	v_mfma_f32_16x16x32_bf16 v[204:207], v[236:239], v[116:119], v[204:207]
	v_mfma_f32_16x16x32_bf16 v[208:211], v[240:243], v[116:119], v[208:211]
	v_mfma_f32_16x16x32_bf16 v[212:215], v[244:247], v[116:119], v[212:215]
	v_mfma_f32_16x16x32_bf16 v[216:219], v[248:251], v[116:119], v[216:219]
	v_mfma_f32_16x16x32_bf16 v[220:223], v[236:239], v[188:191], v[220:223]
	v_mfma_f32_16x16x32_bf16 v[224:227], v[240:243], v[188:191], v[224:227]
	v_mfma_f32_16x16x32_bf16 v[228:231], v[244:247], v[188:191], v[228:231]
	v_mfma_f32_16x16x32_bf16 v[232:235], v[248:251], v[188:191], v[232:235]
	s_waitcnt lgkmcnt(0)
	ds_read_b64_tr_b16 v[236:237], v166
	ds_read_b64_tr_b16 v[238:239], v166 offset:2304
	ds_read_b64_tr_b16 v[240:241], v166 offset:32
	ds_read_b64_tr_b16 v[242:243], v166 offset:2336
	ds_read_b64_tr_b16 v[244:245], v166 offset:64
	ds_read_b64_tr_b16 v[246:247], v166 offset:2368
	ds_read_b64_tr_b16 v[248:249], v166 offset:96
	ds_read_b64_tr_b16 v[250:251], v166 offset:2400
	s_waitcnt lgkmcnt(0)
	s_waitcnt vmcnt(4)
	ds_write_b128 v165, v[64:67]
	ds_write_b128 v165, v[68:71] offset:1152
	ds_write_b128 v165, v[72:75] offset:2304
	ds_write_b128 v165, v[76:79] offset:3456
	v_mfma_f32_16x16x32_bf16 v[204:207], v[236:239], v[120:123], v[204:207]
	v_mfma_f32_16x16x32_bf16 v[208:211], v[240:243], v[120:123], v[208:211]
	v_mfma_f32_16x16x32_bf16 v[212:215], v[244:247], v[120:123], v[212:215]
	v_mfma_f32_16x16x32_bf16 v[216:219], v[248:251], v[120:123], v[216:219]
	v_mfma_f32_16x16x32_bf16 v[220:223], v[236:239], v[192:195], v[220:223]
	v_mfma_f32_16x16x32_bf16 v[224:227], v[240:243], v[192:195], v[224:227]
	v_mfma_f32_16x16x32_bf16 v[228:231], v[244:247], v[192:195], v[228:231]
	v_mfma_f32_16x16x32_bf16 v[232:235], v[248:251], v[192:195], v[232:235]
	s_waitcnt lgkmcnt(0)
	ds_read_b64_tr_b16 v[236:237], v166
	ds_read_b64_tr_b16 v[238:239], v166 offset:2304
	ds_read_b64_tr_b16 v[240:241], v166 offset:32
	ds_read_b64_tr_b16 v[242:243], v166 offset:2336
	ds_read_b64_tr_b16 v[244:245], v166 offset:64
	ds_read_b64_tr_b16 v[246:247], v166 offset:2368
	ds_read_b64_tr_b16 v[248:249], v166 offset:96
	ds_read_b64_tr_b16 v[250:251], v166 offset:2400
	s_waitcnt lgkmcnt(0)
	s_waitcnt vmcnt(0)
	ds_write_b128 v165, v[80:83]
	ds_write_b128 v165, v[84:87] offset:1152
	ds_write_b128 v165, v[88:91] offset:2304
	ds_write_b128 v165, v[92:95] offset:3456
	v_mfma_f32_16x16x32_bf16 v[204:207], v[236:239], v[124:127], v[204:207]
	v_mfma_f32_16x16x32_bf16 v[208:211], v[240:243], v[124:127], v[208:211]
	v_mfma_f32_16x16x32_bf16 v[212:215], v[244:247], v[124:127], v[212:215]
	v_mfma_f32_16x16x32_bf16 v[216:219], v[248:251], v[124:127], v[216:219]
	v_mfma_f32_16x16x32_bf16 v[220:223], v[236:239], v[196:199], v[220:223]
	v_mfma_f32_16x16x32_bf16 v[224:227], v[240:243], v[196:199], v[224:227]
	v_mfma_f32_16x16x32_bf16 v[228:231], v[244:247], v[196:199], v[228:231]
	v_mfma_f32_16x16x32_bf16 v[232:235], v[248:251], v[196:199], v[232:235]
	s_waitcnt lgkmcnt(0)
	ds_read_b64_tr_b16 v[236:237], v166
	ds_read_b64_tr_b16 v[238:239], v166 offset:2304
	ds_read_b64_tr_b16 v[240:241], v166 offset:32
	ds_read_b64_tr_b16 v[242:243], v166 offset:2336
	ds_read_b64_tr_b16 v[244:245], v166 offset:64
	ds_read_b64_tr_b16 v[246:247], v166 offset:2368
	ds_read_b64_tr_b16 v[248:249], v166 offset:96
	ds_read_b64_tr_b16 v[250:251], v166 offset:2400
	s_waitcnt lgkmcnt(0)
	v_mfma_f32_16x16x32_bf16 v[204:207], v[236:239], v[128:131], v[204:207]
	v_mfma_f32_16x16x32_bf16 v[208:211], v[240:243], v[128:131], v[208:211]
	v_mfma_f32_16x16x32_bf16 v[212:215], v[244:247], v[128:131], v[212:215]
	v_mfma_f32_16x16x32_bf16 v[216:219], v[248:251], v[128:131], v[216:219]
	v_mfma_f32_16x16x32_bf16 v[220:223], v[236:239], v[200:203], v[220:223]
	v_mfma_f32_16x16x32_bf16 v[224:227], v[240:243], v[200:203], v[224:227]
	v_mfma_f32_16x16x32_bf16 v[228:231], v[244:247], v[200:203], v[228:231]
	v_mfma_f32_16x16x32_bf16 v[232:235], v[248:251], v[200:203], v[232:235]
	s_add_i32 s2, s42, -64
	v_add_u32_e32 v138, s2, v164
	v_lshlrev_b32_e32 v138, 4, v138
	v_add_u32_e32 v138, s43, v138
	v_and_b32_e32 v139, 3, v138
	v_lshlrev_b32_e32 v139, s13, v139
	v_bfe_u32 v140, v138, 2, 2
	v_add_u32_e32 v139, v139, v140
	v_lshl_add_u32 v139, v139, 7, v162
	v_ashrrev_i32_e32 v138, 4, v138
	v_med3_i32 v138, v138, 0, s14
	v_lshl_add_u32 v138, v138, 9, v139
	global_load_dwordx4 v[64:67], v138, s[22:23]
	s_add_i32 s2, s42, -56
	v_add_u32_e32 v138, s2, v164
	v_lshlrev_b32_e32 v138, 4, v138
	v_add_u32_e32 v138, s43, v138
	v_and_b32_e32 v139, 3, v138
	v_lshlrev_b32_e32 v139, s13, v139
	v_bfe_u32 v140, v138, 2, 2
	v_add_u32_e32 v139, v139, v140
	v_lshl_add_u32 v139, v139, 7, v162
	v_ashrrev_i32_e32 v138, 4, v138
	v_med3_i32 v138, v138, 0, s14
	v_lshl_add_u32 v138, v138, 9, v139
	global_load_dwordx4 v[68:71], v138, s[22:23]
	s_add_i32 s2, s42, -48
	v_add_u32_e32 v138, s2, v164
	v_lshlrev_b32_e32 v138, 4, v138
	v_add_u32_e32 v138, s43, v138
	v_and_b32_e32 v139, 3, v138
	v_lshlrev_b32_e32 v139, s13, v139
	v_bfe_u32 v140, v138, 2, 2
	v_add_u32_e32 v139, v139, v140
	v_lshl_add_u32 v139, v139, 7, v162
	v_ashrrev_i32_e32 v138, 4, v138
	v_med3_i32 v138, v138, 0, s14
	v_lshl_add_u32 v138, v138, 9, v139
	global_load_dwordx4 v[72:75], v138, s[22:23]
	s_add_i32 s2, s42, -40
	v_add_u32_e32 v138, s2, v164
	v_lshlrev_b32_e32 v138, 4, v138
	v_add_u32_e32 v138, s43, v138
	v_and_b32_e32 v139, 3, v138
	v_lshlrev_b32_e32 v139, s13, v139
	v_bfe_u32 v140, v138, 2, 2
	v_add_u32_e32 v139, v139, v140
	v_lshl_add_u32 v139, v139, 7, v162
	v_ashrrev_i32_e32 v138, 4, v138
	v_med3_i32 v138, v138, 0, s14
	v_lshl_add_u32 v138, v138, 9, v139
	global_load_dwordx4 v[76:79], v138, s[22:23]
	s_add_i32 s2, s42, -32
	v_add_u32_e32 v138, s2, v164
	v_lshlrev_b32_e32 v138, 4, v138
	v_add_u32_e32 v138, s43, v138
	v_and_b32_e32 v139, 3, v138
	v_lshlrev_b32_e32 v139, s13, v139
	v_bfe_u32 v140, v138, 2, 2
	v_add_u32_e32 v139, v139, v140
	v_lshl_add_u32 v139, v139, 7, v162
	v_ashrrev_i32_e32 v138, 4, v138
	v_med3_i32 v138, v138, 0, s14
	v_lshl_add_u32 v138, v138, 9, v139
	global_load_dwordx4 v[80:83], v138, s[22:23]
	s_add_i32 s2, s42, -24
	v_add_u32_e32 v138, s2, v164
	v_lshlrev_b32_e32 v138, 4, v138
	v_add_u32_e32 v138, s43, v138
	v_and_b32_e32 v139, 3, v138
	v_lshlrev_b32_e32 v139, s13, v139
	v_bfe_u32 v140, v138, 2, 2
	v_add_u32_e32 v139, v139, v140
	v_lshl_add_u32 v139, v139, 7, v162
	v_ashrrev_i32_e32 v138, 4, v138
	v_med3_i32 v138, v138, 0, s14
	v_lshl_add_u32 v138, v138, 9, v139
	global_load_dwordx4 v[84:87], v138, s[22:23]
	s_add_i32 s2, s42, -16
	v_add_u32_e32 v138, s2, v164
	v_lshlrev_b32_e32 v138, 4, v138
	v_add_u32_e32 v138, s43, v138
	v_and_b32_e32 v139, 3, v138
	v_lshlrev_b32_e32 v139, s13, v139
	v_bfe_u32 v140, v138, 2, 2
	v_add_u32_e32 v139, v139, v140
	v_lshl_add_u32 v139, v139, 7, v162
	v_ashrrev_i32_e32 v138, 4, v138
	v_med3_i32 v138, v138, 0, s14
	v_lshl_add_u32 v138, v138, 9, v139
	global_load_dwordx4 v[88:91], v138, s[22:23]
	s_add_i32 s2, s42, -8
	v_add_u32_e32 v138, s2, v164
	v_lshlrev_b32_e32 v138, 4, v138
	v_add_u32_e32 v138, s43, v138
	v_and_b32_e32 v139, 3, v138
	v_lshlrev_b32_e32 v139, s13, v139
	v_bfe_u32 v140, v138, 2, 2
	v_add_u32_e32 v139, v139, v140
	v_lshl_add_u32 v139, v139, 7, v162
	v_ashrrev_i32_e32 v138, 4, v138
	v_med3_i32 v138, v138, 0, s14
	v_lshl_add_u32 v138, v138, 9, v139
	global_load_dwordx4 v[92:95], v138, s[22:23]
	s_add_i32 s2, s42, 0
	v_add_u32_e32 v138, s2, v164
	v_lshlrev_b32_e32 v138, 4, v138
	v_add_u32_e32 v138, s43, v138
	v_and_b32_e32 v139, 3, v138
	v_lshlrev_b32_e32 v139, s13, v139
	v_bfe_u32 v140, v138, 2, 2
	v_add_u32_e32 v139, v139, v140
	v_lshl_add_u32 v139, v139, 7, v162
	v_ashrrev_i32_e32 v138, 4, v138
	v_med3_i32 v138, v138, 0, s14
	v_lshl_add_u32 v138, v138, 9, v139
	global_load_dwordx4 v[96:99], v138, s[22:23]
	s_add_i32 s2, s42, 8
	v_add_u32_e32 v138, s2, v164
	v_lshlrev_b32_e32 v138, 4, v138
	v_add_u32_e32 v138, s43, v138
	v_and_b32_e32 v139, 3, v138
	v_lshlrev_b32_e32 v139, s13, v139
	v_bfe_u32 v140, v138, 2, 2
	v_add_u32_e32 v139, v139, v140
	v_lshl_add_u32 v139, v139, 7, v162
	v_ashrrev_i32_e32 v138, 4, v138
	v_med3_i32 v138, v138, 0, s14
	v_lshl_add_u32 v138, v138, 9, v139
	global_load_dwordx4 v[100:103], v138, s[22:23]
	s_add_i32 s2, s42, 16
	v_add_u32_e32 v138, s2, v164
	v_lshlrev_b32_e32 v138, 4, v138
	v_add_u32_e32 v138, s43, v138
	v_and_b32_e32 v139, 3, v138
	v_lshlrev_b32_e32 v139, s13, v139
	v_bfe_u32 v140, v138, 2, 2
	v_add_u32_e32 v139, v139, v140
	v_lshl_add_u32 v139, v139, 7, v162
	v_ashrrev_i32_e32 v138, 4, v138
	v_med3_i32 v138, v138, 0, s14
	v_lshl_add_u32 v138, v138, 9, v139
	global_load_dwordx4 v[104:107], v138, s[22:23]
	s_add_i32 s2, s42, 24
	v_add_u32_e32 v138, s2, v164
	v_lshlrev_b32_e32 v138, 4, v138
	v_add_u32_e32 v138, s43, v138
	v_and_b32_e32 v139, 3, v138
	v_lshlrev_b32_e32 v139, s13, v139
	v_bfe_u32 v140, v138, 2, 2
	v_add_u32_e32 v139, v139, v140
	v_lshl_add_u32 v139, v139, 7, v162
	v_ashrrev_i32_e32 v138, 4, v138
	v_med3_i32 v138, v138, 0, s14
	v_lshl_add_u32 v138, v138, 9, v139
	global_load_dwordx4 v[108:111], v138, s[22:23]
	ds_read_b128 v[236:239], v173 offset:0
	ds_read_b128 v[240:243], v173 offset:64
	ds_read_b128 v[244:247], v173 offset:128
	ds_read_b128 v[248:251], v173 offset:192
	ds_read_b32 v142, v174 offset:0
	s_waitcnt lgkmcnt(0)
	v_add_f32_e32 v204, v236, v204
	v_add_f32_e32 v205, v237, v205
	v_add_f32_e32 v206, v238, v206
	v_add_f32_e32 v207, v239, v207
	v_add_f32_e32 v208, v240, v208
	v_add_f32_e32 v209, v241, v209
	v_add_f32_e32 v210, v242, v210
	v_add_f32_e32 v211, v243, v211
	v_add_f32_e32 v212, v244, v212
	v_add_f32_e32 v213, v245, v213
	v_add_f32_e32 v214, v246, v214
	v_add_f32_e32 v215, v247, v215
	v_add_f32_e32 v216, v248, v216
	v_add_f32_e32 v217, v249, v217
	v_add_f32_e32 v218, v250, v218
	v_add_f32_e32 v219, v251, v219
	v_add_f32_e32 v132, v142, v132
	ds_write_b128 v173, v[204:207] offset:0
	ds_write_b128 v173, v[208:211] offset:64
	ds_write_b128 v173, v[212:215] offset:128
	ds_write_b128 v173, v[216:219] offset:192
	ds_write_b32 v174, v132 offset:0
	ds_read_b128 v[236:239], v173 offset:18496
	ds_read_b128 v[240:243], v173 offset:18560
	ds_read_b128 v[244:247], v173 offset:18624
	ds_read_b128 v[248:251], v173 offset:18688
	ds_read_b32 v142, v174 offset:256
	s_waitcnt lgkmcnt(0)
	v_add_f32_e32 v220, v236, v220
	v_add_f32_e32 v221, v237, v221
	v_add_f32_e32 v222, v238, v222
	v_add_f32_e32 v223, v239, v223
	v_add_f32_e32 v224, v240, v224
	v_add_f32_e32 v225, v241, v225
	v_add_f32_e32 v226, v242, v226
	v_add_f32_e32 v227, v243, v227
	v_add_f32_e32 v228, v244, v228
	v_add_f32_e32 v229, v245, v229
	v_add_f32_e32 v230, v246, v230
	v_add_f32_e32 v231, v247, v231
	v_add_f32_e32 v232, v248, v232
	v_add_f32_e32 v233, v249, v233
	v_add_f32_e32 v234, v250, v234
	v_add_f32_e32 v235, v251, v235
	v_add_f32_e32 v133, v142, v133
	ds_write_b128 v173, v[220:223] offset:18496
	ds_write_b128 v173, v[224:227] offset:18560
	ds_write_b128 v173, v[228:231] offset:18624
	ds_write_b128 v173, v[232:235] offset:18688
	ds_write_b32 v174, v133 offset:256
	s_waitcnt lgkmcnt(0)
	s_barrier
	s_mov_b32 s40, s42
	s_mov_b32 s41, s43
	v_mov_b32_e32 v173, v176
	v_mov_b32_e32 v174, v177
	v_mov_b32_e32 v175, v178
	v_mov_b32_e32 v179, v183
	v_mov_b32_e32 v182, v252
	s_lshr_b32 s44, s33, 4
	s_lshr_b32 s42, s15, 4
	s_add_i32 s43, s0, 8
	s_waitcnt vmcnt(12)
	v_mov_b32_e32 v132, 0
	v_mfma_f32_16x16x32_bf16 v[236:239], v[0:3], v[48:51], 0
	v_mfma_f32_16x16x32_bf16 v[236:239], v[4:7], v[52:55], v[236:239]
	v_mfma_f32_16x16x32_bf16 v[240:243], v[8:11], v[48:51], 0
	v_mfma_f32_16x16x32_bf16 v[240:243], v[12:15], v[52:55], v[240:243]
	s_nop 7
	v_min_f32_e32 v152, 0x42a00000, v236
	v_min_f32_e32 v153, 0x42a00000, v237
	v_min_f32_e32 v154, 0x42a00000, v238
	v_min_f32_e32 v155, 0x42a00000, v239
	v_mfma_f32_16x16x32_bf16 v[236:239], v[16:19], v[48:51], 0
	v_mfma_f32_16x16x32_bf16 v[236:239], v[20:23], v[52:55], v[236:239]
	v_add_u32_e32 v136, 0x60, v182
	v_med3_i32 v136, v136, 0, s38
	v_lshl_add_u32 v136, v136, 9, v179
	global_load_dwordx4 v[0:3], v136, s[24:25]
	global_load_dwordx4 v[4:7], v136, s[24:25] offset:64
	v_mul_f32_e32 v152, 0x3fb8aa3b, v152
	v_mul_f32_e32 v153, 0x3fb8aa3b, v153
	v_mul_f32_e32 v154, 0x3fb8aa3b, v154
	v_mul_f32_e32 v155, 0x3fb8aa3b, v155
	v_exp_f32_e32 v152, v152
	v_exp_f32_e32 v153, v153
	v_exp_f32_e32 v154, v154
	v_exp_f32_e32 v155, v155
	v_add_u32_e32 v138, 0, v175
	v_add_u32_e32 v139, 1, v175
	v_add_u32_e32 v140, 2, v175
	v_add_u32_e32 v141, 3, v175
	v_cmp_gt_u32_e64 s[70:71], s44, v138
	v_cmp_gt_u32_e64 s[72:73], s44, v139
	v_cmp_gt_u32_e64 s[74:75], s44, v140
	v_cmp_gt_u32_e64 s[76:77], s44, v141
	v_cndmask_b32_e64 v152, 0, v152, s[54:55]
	v_cndmask_b32_e64 v153, 0, v153, s[56:57]
	v_cndmask_b32_e64 v154, 0, v154, s[58:59]
	v_cndmask_b32_e64 v155, 0, v155, s[60:61]
	v_cndmask_b32_e64 v152, 0, v152, s[70:71]
	v_cndmask_b32_e64 v153, 0, v153, s[72:73]
	v_cndmask_b32_e64 v154, 0, v154, s[74:75]
	v_cndmask_b32_e64 v155, 0, v155, s[76:77]
	v_add_f32_e32 v132, v132, v152
	v_add_f32_e32 v132, v132, v153
	v_add_f32_e32 v132, v132, v154
	v_add_f32_e32 v132, v132, v155
	v_cvt_pk_bf16_f32 v112, v152, v153
	v_cvt_pk_bf16_f32 v113, v154, v155
	v_min_f32_e32 v152, 0x42a00000, v240
	v_min_f32_e32 v153, 0x42a00000, v241
	v_min_f32_e32 v154, 0x42a00000, v242
	v_min_f32_e32 v155, 0x42a00000, v243
	v_mfma_f32_16x16x32_bf16 v[240:243], v[24:27], v[48:51], 0
	v_mfma_f32_16x16x32_bf16 v[240:243], v[28:31], v[52:55], v[240:243]
	v_add_u32_e32 v135, 0x70, v182
	v_med3_i32 v135, v135, 0, s38
	v_lshl_add_u32 v135, v135, 9, v179
	global_load_dwordx4 v[8:11], v135, s[24:25]
	global_load_dwordx4 v[12:15], v135, s[24:25] offset:64
	v_mul_f32_e32 v152, 0x3fb8aa3b, v152
	v_mul_f32_e32 v153, 0x3fb8aa3b, v153
	v_mul_f32_e32 v154, 0x3fb8aa3b, v154
	v_mul_f32_e32 v155, 0x3fb8aa3b, v155
	v_exp_f32_e32 v152, v152
	v_exp_f32_e32 v153, v153
	v_exp_f32_e32 v154, v154
	v_exp_f32_e32 v155, v155
	v_add_u32_e32 v138, 16, v175
	v_add_u32_e32 v139, 17, v175
	v_add_u32_e32 v140, 18, v175
	v_add_u32_e32 v141, 19, v175
	v_cmp_gt_u32_e64 s[70:71], s44, v138
	v_cmp_gt_u32_e64 s[72:73], s44, v139
	v_cmp_gt_u32_e64 s[74:75], s44, v140
	v_cmp_gt_u32_e64 s[76:77], s44, v141
	v_cndmask_b32_e64 v152, 0, v152, s[70:71]
	v_cndmask_b32_e64 v153, 0, v153, s[72:73]
	v_cndmask_b32_e64 v154, 0, v154, s[74:75]
	v_cndmask_b32_e64 v155, 0, v155, s[76:77]
	v_add_f32_e32 v132, v132, v152
	v_add_f32_e32 v132, v132, v153
	v_add_f32_e32 v132, v132, v154
	v_add_f32_e32 v132, v132, v155
	v_cvt_pk_bf16_f32 v114, v152, v153
	v_cvt_pk_bf16_f32 v115, v154, v155
	v_min_f32_e32 v152, 0x42a00000, v236
	v_min_f32_e32 v153, 0x42a00000, v237
	v_min_f32_e32 v154, 0x42a00000, v238
	v_min_f32_e32 v155, 0x42a00000, v239
	v_mfma_f32_16x16x32_bf16 v[236:239], v[32:35], v[48:51], 0
	v_mfma_f32_16x16x32_bf16 v[236:239], v[36:39], v[52:55], v[236:239]
	v_add_u32_e32 v136, 0x80, v182
	v_med3_i32 v136, v136, 0, s38
	v_lshl_add_u32 v136, v136, 9, v179
	global_load_dwordx4 v[16:19], v136, s[24:25]
	global_load_dwordx4 v[20:23], v136, s[24:25] offset:64
	v_mul_f32_e32 v152, 0x3fb8aa3b, v152
	v_mul_f32_e32 v153, 0x3fb8aa3b, v153
	v_mul_f32_e32 v154, 0x3fb8aa3b, v154
	v_mul_f32_e32 v155, 0x3fb8aa3b, v155
	v_exp_f32_e32 v152, v152
	v_exp_f32_e32 v153, v153
	v_exp_f32_e32 v154, v154
	v_exp_f32_e32 v155, v155
	v_add_u32_e32 v138, 32, v175
	v_add_u32_e32 v139, 33, v175
	v_add_u32_e32 v140, 34, v175
	v_add_u32_e32 v141, 35, v175
	v_cmp_gt_u32_e64 s[70:71], s44, v138
	v_cmp_gt_u32_e64 s[72:73], s44, v139
	v_cmp_gt_u32_e64 s[74:75], s44, v140
	v_cmp_gt_u32_e64 s[76:77], s44, v141
	v_cndmask_b32_e64 v152, 0, v152, s[70:71]
	v_cndmask_b32_e64 v153, 0, v153, s[72:73]
	v_cndmask_b32_e64 v154, 0, v154, s[74:75]
	v_cndmask_b32_e64 v155, 0, v155, s[76:77]
	v_add_f32_e32 v132, v132, v152
	v_add_f32_e32 v132, v132, v153
	v_add_f32_e32 v132, v132, v154
	v_add_f32_e32 v132, v132, v155
	v_cvt_pk_bf16_f32 v116, v152, v153
	v_cvt_pk_bf16_f32 v117, v154, v155
	v_min_f32_e32 v152, 0x42a00000, v240
	v_min_f32_e32 v153, 0x42a00000, v241
	v_min_f32_e32 v154, 0x42a00000, v242
	v_min_f32_e32 v155, 0x42a00000, v243
	v_mfma_f32_16x16x32_bf16 v[240:243], v[40:43], v[48:51], 0
	v_mfma_f32_16x16x32_bf16 v[240:243], v[44:47], v[52:55], v[240:243]
	v_mul_f32_e32 v152, 0x3fb8aa3b, v152
	v_mul_f32_e32 v153, 0x3fb8aa3b, v153
	v_mul_f32_e32 v154, 0x3fb8aa3b, v154
	v_mul_f32_e32 v155, 0x3fb8aa3b, v155
	v_exp_f32_e32 v152, v152
	v_exp_f32_e32 v153, v153
	v_exp_f32_e32 v154, v154
	v_exp_f32_e32 v155, v155
	v_add_u32_e32 v138, 48, v175
	v_add_u32_e32 v139, 49, v175
	v_add_u32_e32 v140, 50, v175
	v_add_u32_e32 v141, 51, v175
	v_cmp_gt_u32_e64 s[70:71], s44, v138
	v_cmp_gt_u32_e64 s[72:73], s44, v139
	v_cmp_gt_u32_e64 s[74:75], s44, v140
	v_cmp_gt_u32_e64 s[76:77], s44, v141
	v_cndmask_b32_e64 v152, 0, v152, s[70:71]
	v_cndmask_b32_e64 v153, 0, v153, s[72:73]
	v_cndmask_b32_e64 v154, 0, v154, s[74:75]
	v_cndmask_b32_e64 v155, 0, v155, s[76:77]
	v_add_f32_e32 v132, v132, v152
	v_add_f32_e32 v132, v132, v153
	v_add_f32_e32 v132, v132, v154
	v_add_f32_e32 v132, v132, v155
	v_cvt_pk_bf16_f32 v118, v152, v153
	v_cvt_pk_bf16_f32 v119, v154, v155
	v_min_f32_e32 v152, 0x42a00000, v236
	v_min_f32_e32 v153, 0x42a00000, v237
	v_min_f32_e32 v154, 0x42a00000, v238
	v_min_f32_e32 v155, 0x42a00000, v239
	s_waitcnt vmcnt(4)
	v_mfma_f32_16x16x32_bf16 v[236:239], v[0:3], v[48:51], 0
	v_mfma_f32_16x16x32_bf16 v[236:239], v[4:7], v[52:55], v[236:239]
	v_mul_f32_e32 v152, 0x3fb8aa3b, v152
	v_mul_f32_e32 v153, 0x3fb8aa3b, v153
	v_mul_f32_e32 v154, 0x3fb8aa3b, v154
	v_mul_f32_e32 v155, 0x3fb8aa3b, v155
	v_exp_f32_e32 v152, v152
	v_exp_f32_e32 v153, v153
	v_exp_f32_e32 v154, v154
	v_exp_f32_e32 v155, v155
	v_add_u32_e32 v138, 64, v175
	v_add_u32_e32 v139, 0x41, v175
	v_add_u32_e32 v140, 0x42, v175
	v_add_u32_e32 v141, 0x43, v175
	v_cmp_gt_u32_e64 s[70:71], s44, v138
	v_cmp_gt_u32_e64 s[72:73], s44, v139
	v_cmp_gt_u32_e64 s[74:75], s44, v140
	v_cmp_gt_u32_e64 s[76:77], s44, v141
	v_cndmask_b32_e64 v152, 0, v152, s[70:71]
	v_cndmask_b32_e64 v153, 0, v153, s[72:73]
	v_cndmask_b32_e64 v154, 0, v154, s[74:75]
	v_cndmask_b32_e64 v155, 0, v155, s[76:77]
	v_add_f32_e32 v132, v132, v152
	v_add_f32_e32 v132, v132, v153
	v_add_f32_e32 v132, v132, v154
	v_add_f32_e32 v132, v132, v155
	v_cvt_pk_bf16_f32 v120, v152, v153
	v_cvt_pk_bf16_f32 v121, v154, v155
	v_min_f32_e32 v152, 0x42a00000, v240
	v_min_f32_e32 v153, 0x42a00000, v241
	v_min_f32_e32 v154, 0x42a00000, v242
	v_min_f32_e32 v155, 0x42a00000, v243
	s_waitcnt vmcnt(2)
	v_mfma_f32_16x16x32_bf16 v[240:243], v[8:11], v[48:51], 0
	v_mfma_f32_16x16x32_bf16 v[240:243], v[12:15], v[52:55], v[240:243]
	v_mul_f32_e32 v152, 0x3fb8aa3b, v152
	v_mul_f32_e32 v153, 0x3fb8aa3b, v153
	v_mul_f32_e32 v154, 0x3fb8aa3b, v154
	v_mul_f32_e32 v155, 0x3fb8aa3b, v155
	v_exp_f32_e32 v152, v152
	v_exp_f32_e32 v153, v153
	v_exp_f32_e32 v154, v154
	v_exp_f32_e32 v155, v155
	v_add_u32_e32 v138, 0x50, v175
	v_add_u32_e32 v139, 0x51, v175
	v_add_u32_e32 v140, 0x52, v175
	v_add_u32_e32 v141, 0x53, v175
	v_cmp_gt_u32_e64 s[70:71], s44, v138
	v_cmp_gt_u32_e64 s[72:73], s44, v139
	v_cmp_gt_u32_e64 s[74:75], s44, v140
	v_cmp_gt_u32_e64 s[76:77], s44, v141
	v_cndmask_b32_e64 v152, 0, v152, s[70:71]
	v_cndmask_b32_e64 v153, 0, v153, s[72:73]
	v_cndmask_b32_e64 v154, 0, v154, s[74:75]
	v_cndmask_b32_e64 v155, 0, v155, s[76:77]
	v_add_f32_e32 v132, v132, v152
	v_add_f32_e32 v132, v132, v153
	v_add_f32_e32 v132, v132, v154
	v_add_f32_e32 v132, v132, v155
	v_cvt_pk_bf16_f32 v122, v152, v153
	v_cvt_pk_bf16_f32 v123, v154, v155
	v_min_f32_e32 v152, 0x42a00000, v236
	v_min_f32_e32 v153, 0x42a00000, v237
	v_min_f32_e32 v154, 0x42a00000, v238
	v_min_f32_e32 v155, 0x42a00000, v239
	s_waitcnt vmcnt(0)
	v_mfma_f32_16x16x32_bf16 v[236:239], v[16:19], v[48:51], 0
	v_mfma_f32_16x16x32_bf16 v[236:239], v[20:23], v[52:55], v[236:239]
	v_mul_f32_e32 v152, 0x3fb8aa3b, v152
	v_mul_f32_e32 v153, 0x3fb8aa3b, v153
	v_mul_f32_e32 v154, 0x3fb8aa3b, v154
	v_mul_f32_e32 v155, 0x3fb8aa3b, v155
	v_exp_f32_e32 v152, v152
	v_exp_f32_e32 v153, v153
	v_exp_f32_e32 v154, v154
	v_exp_f32_e32 v155, v155
	v_add_u32_e32 v138, 0x60, v175
	v_add_u32_e32 v139, 0x61, v175
	v_add_u32_e32 v140, 0x62, v175
	v_add_u32_e32 v141, 0x63, v175
	v_cmp_gt_u32_e64 s[70:71], s44, v138
	v_cmp_gt_u32_e64 s[72:73], s44, v139
	v_cmp_gt_u32_e64 s[74:75], s44, v140
	v_cmp_gt_u32_e64 s[76:77], s44, v141
	v_cndmask_b32_e64 v152, 0, v152, s[70:71]
	v_cndmask_b32_e64 v153, 0, v153, s[72:73]
	v_cndmask_b32_e64 v154, 0, v154, s[74:75]
	v_cndmask_b32_e64 v155, 0, v155, s[76:77]
	v_add_f32_e32 v132, v132, v152
	v_add_f32_e32 v132, v132, v153
	v_add_f32_e32 v132, v132, v154
	v_add_f32_e32 v132, v132, v155
	v_cvt_pk_bf16_f32 v124, v152, v153
	v_cvt_pk_bf16_f32 v125, v154, v155
	v_min_f32_e32 v152, 0x42a00000, v240
	v_min_f32_e32 v153, 0x42a00000, v241
	v_min_f32_e32 v154, 0x42a00000, v242
	v_min_f32_e32 v155, 0x42a00000, v243
	v_mul_f32_e32 v152, 0x3fb8aa3b, v152
	v_mul_f32_e32 v153, 0x3fb8aa3b, v153
	v_mul_f32_e32 v154, 0x3fb8aa3b, v154
	v_mul_f32_e32 v155, 0x3fb8aa3b, v155
	v_exp_f32_e32 v152, v152
	v_exp_f32_e32 v153, v153
	v_exp_f32_e32 v154, v154
	v_exp_f32_e32 v155, v155
	v_add_u32_e32 v138, 0x70, v175
	v_add_u32_e32 v139, 0x71, v175
	v_add_u32_e32 v140, 0x72, v175
	v_add_u32_e32 v141, 0x73, v175
	v_cmp_gt_u32_e64 s[70:71], s44, v138
	v_cmp_gt_u32_e64 s[72:73], s44, v139
	v_cmp_gt_u32_e64 s[74:75], s44, v140
	v_cmp_gt_u32_e64 s[76:77], s44, v141
	v_cndmask_b32_e64 v152, 0, v152, s[70:71]
	v_cndmask_b32_e64 v153, 0, v153, s[72:73]
	v_cndmask_b32_e64 v154, 0, v154, s[74:75]
	v_cndmask_b32_e64 v155, 0, v155, s[76:77]
	v_add_f32_e32 v132, v132, v152
	v_add_f32_e32 v132, v132, v153
	v_add_f32_e32 v132, v132, v154
	v_add_f32_e32 v132, v132, v155
	v_cvt_pk_bf16_f32 v126, v152, v153
	v_cvt_pk_bf16_f32 v127, v154, v155
	v_min_f32_e32 v152, 0x42a00000, v236
	v_min_f32_e32 v153, 0x42a00000, v237
	v_min_f32_e32 v154, 0x42a00000, v238
	v_min_f32_e32 v155, 0x42a00000, v239
	v_mul_f32_e32 v152, 0x3fb8aa3b, v152
	v_mul_f32_e32 v153, 0x3fb8aa3b, v153
	v_mul_f32_e32 v154, 0x3fb8aa3b, v154
	v_mul_f32_e32 v155, 0x3fb8aa3b, v155
	v_exp_f32_e32 v152, v152
	v_exp_f32_e32 v153, v153
	v_exp_f32_e32 v154, v154
	v_exp_f32_e32 v155, v155
	v_add_u32_e32 v138, 0x80, v175
	v_add_u32_e32 v139, 0x81, v175
	v_add_u32_e32 v140, 0x82, v175
	v_add_u32_e32 v141, 0x83, v175
	v_cmp_gt_u32_e64 s[70:71], s44, v138
	v_cmp_gt_u32_e64 s[72:73], s44, v139
	v_cmp_gt_u32_e64 s[74:75], s44, v140
	v_cmp_gt_u32_e64 s[76:77], s44, v141
	v_cndmask_b32_e64 v152, 0, v152, s[62:63]
	v_cndmask_b32_e64 v153, 0, v153, s[64:65]
	v_cndmask_b32_e64 v154, 0, v154, s[66:67]
	v_cndmask_b32_e64 v155, 0, v155, s[68:69]
	v_cndmask_b32_e64 v152, 0, v152, s[70:71]
	v_cndmask_b32_e64 v153, 0, v153, s[72:73]
	v_cndmask_b32_e64 v154, 0, v154, s[74:75]
	v_cndmask_b32_e64 v155, 0, v155, s[76:77]
	v_add_f32_e32 v132, v132, v152
	v_add_f32_e32 v132, v132, v153
	v_add_f32_e32 v132, v132, v154
	v_add_f32_e32 v132, v132, v155
	v_cvt_pk_bf16_f32 v128, v152, v153
	v_cvt_pk_bf16_f32 v129, v154, v155
	v_add_u32_e32 v134, s42, v160
	v_lshlrev_b32_e32 v134, 4, v134
	v_add_u32_e32 v134, s43, v134
	v_subrev_u32_e32 v135, s15, v134
	v_lshrrev_b32_e32 v136, 4, v135
	v_add_u32_e32 v136, v136, v135
	v_mad_u32_u24 v176, v136, s79, v161
	v_lshl_add_u32 v177, v135, 2, s80
	s_sub_i32 s2, s42, 64
	v_add_u32_e32 v178, s2, v169
	v_and_b32_e32 v135, 3, v134
	v_lshlrev_b32_e32 v135, s13, v135
	v_lshrrev_b32_e32 v136, 2, v134
	v_add_u32_e32 v135, v135, v136
	v_lshl_add_u32 v135, v135, 7, v161
	global_load_dwordx4 v[48:51], v135, s[18:19]
	global_load_dwordx4 v[52:55], v135, s[18:19] offset:64
	v_subrev_u32_e32 v134, 0x400, v134
	v_and_b32_e32 v137, 3, v134
	v_lshlrev_b32_e32 v137, s13, v137
	v_bfe_u32 v135, v134, 2, 2
	v_add_u32_e32 v137, v137, v135
	v_lshl_add_u32 v183, v137, 7, v161
	v_ashrrev_i32_e32 v252, 4, v134
	v_med3_i32 v136, v252, 0, s14
	v_lshl_add_u32 v136, v136, 9, v183
	global_load_dwordx4 v[0:3], v136, s[20:21]
	global_load_dwordx4 v[4:7], v136, s[20:21] offset:64
	v_add_u32_e32 v135, 16, v252
	v_med3_i32 v135, v135, 0, s14
	v_lshl_add_u32 v135, v135, 9, v183
	global_load_dwordx4 v[8:11], v135, s[20:21]
	global_load_dwordx4 v[12:15], v135, s[20:21] offset:64
	v_add_u32_e32 v136, 32, v252
	v_med3_i32 v136, v136, 0, s14
	v_lshl_add_u32 v136, v136, 9, v183
	global_load_dwordx4 v[16:19], v136, s[20:21]
	global_load_dwordx4 v[20:23], v136, s[20:21] offset:64
	v_add_u32_e32 v135, 48, v252
	v_med3_i32 v135, v135, 0, s14
	v_lshl_add_u32 v135, v135, 9, v183
	global_load_dwordx4 v[24:27], v135, s[20:21]
	global_load_dwordx4 v[28:31], v135, s[20:21] offset:64
	v_add_u32_e32 v136, 64, v252
	v_med3_i32 v136, v136, 0, s14
	v_lshl_add_u32 v136, v136, 9, v183
	global_load_dwordx4 v[32:35], v136, s[20:21]
	global_load_dwordx4 v[36:39], v136, s[20:21] offset:64
	v_add_u32_e32 v135, 0x50, v252
	v_med3_i32 v135, v135, 0, s14
	v_lshl_add_u32 v135, v135, 9, v183
	global_load_dwordx4 v[40:43], v135, s[20:21]
	global_load_dwordx4 v[44:47], v135, s[20:21] offset:64
	ds_bpermute_b32 v142, v167, v132
	s_waitcnt lgkmcnt(0)
	v_add_f32_e32 v132, v132, v142
	ds_bpermute_b32 v142, v168, v132
	s_waitcnt lgkmcnt(0)
	v_add_f32_e32 v132, v132, v142
	s_waitcnt vmcnt(14)
	ds_write_b128 v165, v[64:67]
	ds_write_b128 v165, v[68:71] offset:1152
	ds_write_b128 v165, v[72:75] offset:2304
	ds_write_b128 v165, v[76:79] offset:3456
	s_waitcnt lgkmcnt(0)
	ds_read_b64_tr_b16 v[236:237], v166
	ds_read_b64_tr_b16 v[238:239], v166 offset:2304
	ds_read_b64_tr_b16 v[240:241], v166 offset:32
	ds_read_b64_tr_b16 v[242:243], v166 offset:2336
	ds_read_b64_tr_b16 v[244:245], v166 offset:64
	ds_read_b64_tr_b16 v[246:247], v166 offset:2368
	ds_read_b64_tr_b16 v[248:249], v166 offset:96
	ds_read_b64_tr_b16 v[250:251], v166 offset:2400
	s_waitcnt lgkmcnt(0)
	s_add_i32 s2, s40, 32
	v_add_u32_e32 v138, s2, v164
	v_lshlrev_b32_e32 v138, 4, v138
	v_add_u32_e32 v138, s41, v138
	v_and_b32_e32 v139, 3, v138
	v_lshlrev_b32_e32 v139, s39, v139
	v_bfe_u32 v140, v138, 2, 2
	v_add_u32_e32 v139, v139, v140
	v_lshl_add_u32 v139, v139, 7, v162
	v_ashrrev_i32_e32 v138, 4, v138
	v_med3_i32 v138, v138, 0, s38
	v_lshl_add_u32 v138, v138, 9, v139
	global_load_dwordx4 v[64:67], v138, s[26:27]
	s_add_i32 s2, s40, 40
	v_add_u32_e32 v138, s2, v164
	v_lshlrev_b32_e32 v138, 4, v138
	v_add_u32_e32 v138, s41, v138
	v_and_b32_e32 v139, 3, v138
	v_lshlrev_b32_e32 v139, s39, v139
	v_bfe_u32 v140, v138, 2, 2
	v_add_u32_e32 v139, v139, v140
	v_lshl_add_u32 v139, v139, 7, v162
	v_ashrrev_i32_e32 v138, 4, v138
	v_med3_i32 v138, v138, 0, s38
	v_lshl_add_u32 v138, v138, 9, v139
	global_load_dwordx4 v[68:71], v138, s[26:27]
	s_add_i32 s2, s40, 48
	v_add_u32_e32 v138, s2, v164
	v_lshlrev_b32_e32 v138, 4, v138
	v_add_u32_e32 v138, s41, v138
	v_and_b32_e32 v139, 3, v138
	v_lshlrev_b32_e32 v139, s39, v139
	v_bfe_u32 v140, v138, 2, 2
	v_add_u32_e32 v139, v139, v140
	v_lshl_add_u32 v139, v139, 7, v162
	v_ashrrev_i32_e32 v138, 4, v138
	v_med3_i32 v138, v138, 0, s38
	v_lshl_add_u32 v138, v138, 9, v139
	global_load_dwordx4 v[72:75], v138, s[26:27]
	s_add_i32 s2, s40, 56
	v_add_u32_e32 v138, s2, v164
	v_lshlrev_b32_e32 v138, 4, v138
	v_add_u32_e32 v138, s41, v138
	v_and_b32_e32 v139, 3, v138
	v_lshlrev_b32_e32 v139, s39, v139
	v_bfe_u32 v140, v138, 2, 2
	v_add_u32_e32 v139, v139, v140
	v_lshl_add_u32 v139, v139, 7, v162
	v_ashrrev_i32_e32 v138, 4, v138
	v_med3_i32 v138, v138, 0, s38
	v_lshl_add_u32 v138, v138, 9, v139
	global_load_dwordx4 v[76:79], v138, s[26:27]
	ds_write_b128 v165, v[80:83]
	ds_write_b128 v165, v[84:87] offset:1152
	ds_write_b128 v165, v[88:91] offset:2304
	ds_write_b128 v165, v[92:95] offset:3456
	v_mfma_f32_16x16x32_bf16 v[204:207], v[236:239], v[112:115], 0
	v_mfma_f32_16x16x32_bf16 v[208:211], v[240:243], v[112:115], 0
	v_mfma_f32_16x16x32_bf16 v[212:215], v[244:247], v[112:115], 0
	v_mfma_f32_16x16x32_bf16 v[216:219], v[248:251], v[112:115], 0
	s_waitcnt lgkmcnt(0)
	ds_read_b64_tr_b16 v[236:237], v166
	ds_read_b64_tr_b16 v[238:239], v166 offset:2304
	ds_read_b64_tr_b16 v[240:241], v166 offset:32
	ds_read_b64_tr_b16 v[242:243], v166 offset:2336
	ds_read_b64_tr_b16 v[244:245], v166 offset:64
	ds_read_b64_tr_b16 v[246:247], v166 offset:2368
	ds_read_b64_tr_b16 v[248:249], v166 offset:96
	ds_read_b64_tr_b16 v[250:251], v166 offset:2400
	s_waitcnt lgkmcnt(0)
	s_add_i32 s2, s40, 64
	v_add_u32_e32 v138, s2, v164
	v_lshlrev_b32_e32 v138, 4, v138
	v_add_u32_e32 v138, s41, v138
	v_and_b32_e32 v139, 3, v138
	v_lshlrev_b32_e32 v139, s39, v139
	v_bfe_u32 v140, v138, 2, 2
	v_add_u32_e32 v139, v139, v140
	v_lshl_add_u32 v139, v139, 7, v162
	v_ashrrev_i32_e32 v138, 4, v138
	v_med3_i32 v138, v138, 0, s38
	v_lshl_add_u32 v138, v138, 9, v139
	global_load_dwordx4 v[80:83], v138, s[26:27]
	s_add_i32 s2, s40, 72
	v_add_u32_e32 v138, s2, v164
	v_lshlrev_b32_e32 v138, 4, v138
	v_add_u32_e32 v138, s41, v138
	v_and_b32_e32 v139, 3, v138
	v_lshlrev_b32_e32 v139, s39, v139
	v_bfe_u32 v140, v138, 2, 2
	v_add_u32_e32 v139, v139, v140
	v_lshl_add_u32 v139, v139, 7, v162
	v_ashrrev_i32_e32 v138, 4, v138
	v_med3_i32 v138, v138, 0, s38
	v_lshl_add_u32 v138, v138, 9, v139
	global_load_dwordx4 v[84:87], v138, s[26:27]
	ds_write_b128 v165, v[96:99]
	ds_write_b128 v165, v[100:103] offset:1152
	ds_write_b128 v165, v[104:107] offset:2304
	ds_write_b128 v165, v[108:111] offset:3456
	v_mfma_f32_16x16x32_bf16 v[204:207], v[236:239], v[116:119], v[204:207]
	v_mfma_f32_16x16x32_bf16 v[208:211], v[240:243], v[116:119], v[208:211]
	v_mfma_f32_16x16x32_bf16 v[212:215], v[244:247], v[116:119], v[212:215]
	v_mfma_f32_16x16x32_bf16 v[216:219], v[248:251], v[116:119], v[216:219]
	s_waitcnt lgkmcnt(0)
	ds_read_b64_tr_b16 v[236:237], v166
	ds_read_b64_tr_b16 v[238:239], v166 offset:2304
	ds_read_b64_tr_b16 v[240:241], v166 offset:32
	ds_read_b64_tr_b16 v[242:243], v166 offset:2336
	ds_read_b64_tr_b16 v[244:245], v166 offset:64
	ds_read_b64_tr_b16 v[246:247], v166 offset:2368
	ds_read_b64_tr_b16 v[248:249], v166 offset:96
	ds_read_b64_tr_b16 v[250:251], v166 offset:2400
	s_waitcnt lgkmcnt(0)
	s_waitcnt vmcnt(2)
	ds_write_b128 v165, v[64:67]
	ds_write_b128 v165, v[68:71] offset:1152
	ds_write_b128 v165, v[72:75] offset:2304
	ds_write_b128 v165, v[76:79] offset:3456
	v_mfma_f32_16x16x32_bf16 v[204:207], v[236:239], v[120:123], v[204:207]
	v_mfma_f32_16x16x32_bf16 v[208:211], v[240:243], v[120:123], v[208:211]
	v_mfma_f32_16x16x32_bf16 v[212:215], v[244:247], v[120:123], v[212:215]
	v_mfma_f32_16x16x32_bf16 v[216:219], v[248:251], v[120:123], v[216:219]
	s_waitcnt lgkmcnt(0)
	ds_read_b64_tr_b16 v[236:237], v166
	ds_read_b64_tr_b16 v[238:239], v166 offset:2304
	ds_read_b64_tr_b16 v[240:241], v166 offset:32
	ds_read_b64_tr_b16 v[242:243], v166 offset:2336
	ds_read_b64_tr_b16 v[244:245], v166 offset:64
	ds_read_b64_tr_b16 v[246:247], v166 offset:2368
	ds_read_b64_tr_b16 v[248:249], v166 offset:96
	ds_read_b64_tr_b16 v[250:251], v166 offset:2400
	s_waitcnt lgkmcnt(0)
	s_waitcnt vmcnt(0)
	ds_write_b128 v165, v[80:83]
	ds_write_b128 v165, v[84:87] offset:1152
	v_mfma_f32_16x16x32_bf16 v[204:207], v[236:239], v[124:127], v[204:207]
	v_mfma_f32_16x16x32_bf16 v[208:211], v[240:243], v[124:127], v[208:211]
	v_mfma_f32_16x16x32_bf16 v[212:215], v[244:247], v[124:127], v[212:215]
	v_mfma_f32_16x16x32_bf16 v[216:219], v[248:251], v[124:127], v[216:219]
	s_waitcnt lgkmcnt(0)
	ds_read_b64_tr_b16 v[236:237], v166
	ds_read_b64_tr_b16 v[238:239], v166 offset:2304
	ds_read_b64_tr_b16 v[240:241], v166 offset:32
	ds_read_b64_tr_b16 v[242:243], v166 offset:2336
	ds_read_b64_tr_b16 v[244:245], v166 offset:64
	ds_read_b64_tr_b16 v[246:247], v166 offset:2368
	ds_read_b64_tr_b16 v[248:249], v166 offset:96
	ds_read_b64_tr_b16 v[250:251], v166 offset:2400
	s_waitcnt lgkmcnt(0)
	v_mfma_f32_16x16x32_bf16 v[204:207], v[236:239], v[128:131], v[204:207]
	v_mfma_f32_16x16x32_bf16 v[208:211], v[240:243], v[128:131], v[208:211]
	v_mfma_f32_16x16x32_bf16 v[212:215], v[244:247], v[128:131], v[212:215]
	v_mfma_f32_16x16x32_bf16 v[216:219], v[248:251], v[128:131], v[216:219]
	s_add_i32 s2, s42, -64
	v_add_u32_e32 v138, s2, v164
	v_lshlrev_b32_e32 v138, 4, v138
	v_add_u32_e32 v138, s43, v138
	v_and_b32_e32 v139, 3, v138
	v_lshlrev_b32_e32 v139, s13, v139
	v_bfe_u32 v140, v138, 2, 2
	v_add_u32_e32 v139, v139, v140
	v_lshl_add_u32 v139, v139, 7, v162
	v_ashrrev_i32_e32 v138, 4, v138
	v_med3_i32 v138, v138, 0, s14
	v_lshl_add_u32 v138, v138, 9, v139
	global_load_dwordx4 v[64:67], v138, s[22:23]
	s_add_i32 s2, s42, -56
	v_add_u32_e32 v138, s2, v164
	v_lshlrev_b32_e32 v138, 4, v138
	v_add_u32_e32 v138, s43, v138
	v_and_b32_e32 v139, 3, v138
	v_lshlrev_b32_e32 v139, s13, v139
	v_bfe_u32 v140, v138, 2, 2
	v_add_u32_e32 v139, v139, v140
	v_lshl_add_u32 v139, v139, 7, v162
	v_ashrrev_i32_e32 v138, 4, v138
	v_med3_i32 v138, v138, 0, s14
	v_lshl_add_u32 v138, v138, 9, v139
	global_load_dwordx4 v[68:71], v138, s[22:23]
	s_add_i32 s2, s42, -48
	v_add_u32_e32 v138, s2, v164
	v_lshlrev_b32_e32 v138, 4, v138
	v_add_u32_e32 v138, s43, v138
	v_and_b32_e32 v139, 3, v138
	v_lshlrev_b32_e32 v139, s13, v139
	v_bfe_u32 v140, v138, 2, 2
	v_add_u32_e32 v139, v139, v140
	v_lshl_add_u32 v139, v139, 7, v162
	v_ashrrev_i32_e32 v138, 4, v138
	v_med3_i32 v138, v138, 0, s14
	v_lshl_add_u32 v138, v138, 9, v139
	global_load_dwordx4 v[72:75], v138, s[22:23]
	s_add_i32 s2, s42, -40
	v_add_u32_e32 v138, s2, v164
	v_lshlrev_b32_e32 v138, 4, v138
	v_add_u32_e32 v138, s43, v138
	v_and_b32_e32 v139, 3, v138
	v_lshlrev_b32_e32 v139, s13, v139
	v_bfe_u32 v140, v138, 2, 2
	v_add_u32_e32 v139, v139, v140
	v_lshl_add_u32 v139, v139, 7, v162
	v_ashrrev_i32_e32 v138, 4, v138
	v_med3_i32 v138, v138, 0, s14
	v_lshl_add_u32 v138, v138, 9, v139
	global_load_dwordx4 v[76:79], v138, s[22:23]
	s_add_i32 s2, s42, -32
	v_add_u32_e32 v138, s2, v164
	v_lshlrev_b32_e32 v138, 4, v138
	v_add_u32_e32 v138, s43, v138
	v_and_b32_e32 v139, 3, v138
	v_lshlrev_b32_e32 v139, s13, v139
	v_bfe_u32 v140, v138, 2, 2
	v_add_u32_e32 v139, v139, v140
	v_lshl_add_u32 v139, v139, 7, v162
	v_ashrrev_i32_e32 v138, 4, v138
	v_med3_i32 v138, v138, 0, s14
	v_lshl_add_u32 v138, v138, 9, v139
	global_load_dwordx4 v[80:83], v138, s[22:23]
	s_add_i32 s2, s42, -24
	v_add_u32_e32 v138, s2, v164
	v_lshlrev_b32_e32 v138, 4, v138
	v_add_u32_e32 v138, s43, v138
	v_and_b32_e32 v139, 3, v138
	v_lshlrev_b32_e32 v139, s13, v139
	v_bfe_u32 v140, v138, 2, 2
	v_add_u32_e32 v139, v139, v140
	v_lshl_add_u32 v139, v139, 7, v162
	v_ashrrev_i32_e32 v138, 4, v138
	v_med3_i32 v138, v138, 0, s14
	v_lshl_add_u32 v138, v138, 9, v139
	global_load_dwordx4 v[84:87], v138, s[22:23]
	s_add_i32 s2, s42, -16
	v_add_u32_e32 v138, s2, v164
	v_lshlrev_b32_e32 v138, 4, v138
	v_add_u32_e32 v138, s43, v138
	v_and_b32_e32 v139, 3, v138
	v_lshlrev_b32_e32 v139, s13, v139
	v_bfe_u32 v140, v138, 2, 2
	v_add_u32_e32 v139, v139, v140
	v_lshl_add_u32 v139, v139, 7, v162
	v_ashrrev_i32_e32 v138, 4, v138
	v_med3_i32 v138, v138, 0, s14
	v_lshl_add_u32 v138, v138, 9, v139
	global_load_dwordx4 v[88:91], v138, s[22:23]
	s_add_i32 s2, s42, -8
	v_add_u32_e32 v138, s2, v164
	v_lshlrev_b32_e32 v138, 4, v138
	v_add_u32_e32 v138, s43, v138
	v_and_b32_e32 v139, 3, v138
	v_lshlrev_b32_e32 v139, s13, v139
	v_bfe_u32 v140, v138, 2, 2
	v_add_u32_e32 v139, v139, v140
	v_lshl_add_u32 v139, v139, 7, v162
	v_ashrrev_i32_e32 v138, 4, v138
	v_med3_i32 v138, v138, 0, s14
	v_lshl_add_u32 v138, v138, 9, v139
	global_load_dwordx4 v[92:95], v138, s[22:23]
	s_add_i32 s2, s42, 0
	v_add_u32_e32 v138, s2, v164
	v_lshlrev_b32_e32 v138, 4, v138
	v_add_u32_e32 v138, s43, v138
	v_and_b32_e32 v139, 3, v138
	v_lshlrev_b32_e32 v139, s13, v139
	v_bfe_u32 v140, v138, 2, 2
	v_add_u32_e32 v139, v139, v140
	v_lshl_add_u32 v139, v139, 7, v162
	v_ashrrev_i32_e32 v138, 4, v138
	v_med3_i32 v138, v138, 0, s14
	v_lshl_add_u32 v138, v138, 9, v139
	global_load_dwordx4 v[96:99], v138, s[22:23]
	s_add_i32 s2, s42, 8
	v_add_u32_e32 v138, s2, v164
	v_lshlrev_b32_e32 v138, 4, v138
	v_add_u32_e32 v138, s43, v138
	v_and_b32_e32 v139, 3, v138
	v_lshlrev_b32_e32 v139, s13, v139
	v_bfe_u32 v140, v138, 2, 2
	v_add_u32_e32 v139, v139, v140
	v_lshl_add_u32 v139, v139, 7, v162
	v_ashrrev_i32_e32 v138, 4, v138
	v_med3_i32 v138, v138, 0, s14
	v_lshl_add_u32 v138, v138, 9, v139
	global_load_dwordx4 v[100:103], v138, s[22:23]
	s_add_i32 s2, s42, 16
	v_add_u32_e32 v138, s2, v164
	v_lshlrev_b32_e32 v138, 4, v138
	v_add_u32_e32 v138, s43, v138
	v_and_b32_e32 v139, 3, v138
	v_lshlrev_b32_e32 v139, s13, v139
	v_bfe_u32 v140, v138, 2, 2
	v_add_u32_e32 v139, v139, v140
	v_lshl_add_u32 v139, v139, 7, v162
	v_ashrrev_i32_e32 v138, 4, v138
	v_med3_i32 v138, v138, 0, s14
	v_lshl_add_u32 v138, v138, 9, v139
	global_load_dwordx4 v[104:107], v138, s[22:23]
	s_add_i32 s2, s42, 24
	v_add_u32_e32 v138, s2, v164
	v_lshlrev_b32_e32 v138, 4, v138
	v_add_u32_e32 v138, s43, v138
	v_and_b32_e32 v139, 3, v138
	v_lshlrev_b32_e32 v139, s13, v139
	v_bfe_u32 v140, v138, 2, 2
	v_add_u32_e32 v139, v139, v140
	v_lshl_add_u32 v139, v139, 7, v162
	v_ashrrev_i32_e32 v138, 4, v138
	v_med3_i32 v138, v138, 0, s14
	v_lshl_add_u32 v138, v138, 9, v139
	global_load_dwordx4 v[108:111], v138, s[22:23]
	ds_read_b128 v[236:239], v173 offset:0
	ds_read_b128 v[240:243], v173 offset:64
	ds_read_b128 v[244:247], v173 offset:128
	ds_read_b128 v[248:251], v173 offset:192
	ds_read_b32 v142, v174 offset:0
	s_waitcnt lgkmcnt(0)
	v_add_f32_e32 v204, v236, v204
	v_add_f32_e32 v205, v237, v205
	v_add_f32_e32 v206, v238, v206
	v_add_f32_e32 v207, v239, v207
	v_add_f32_e32 v208, v240, v208
	v_add_f32_e32 v209, v241, v209
	v_add_f32_e32 v210, v242, v210
	v_add_f32_e32 v211, v243, v211
	v_add_f32_e32 v212, v244, v212
	v_add_f32_e32 v213, v245, v213
	v_add_f32_e32 v214, v246, v214
	v_add_f32_e32 v215, v247, v215
	v_add_f32_e32 v216, v248, v216
	v_add_f32_e32 v217, v249, v217
	v_add_f32_e32 v218, v250, v218
	v_add_f32_e32 v219, v251, v219
	v_add_f32_e32 v132, v142, v132
	ds_write_b128 v173, v[204:207] offset:0
	ds_write_b128 v173, v[208:211] offset:64
	ds_write_b128 v173, v[212:215] offset:128
	ds_write_b128 v173, v[216:219] offset:192
	ds_write_b32 v174, v132 offset:0
	s_mov_b32 s40, s42
	s_mov_b32 s41, s43
	v_mov_b32_e32 v173, v176
	v_mov_b32_e32 v174, v177
	v_mov_b32_e32 v175, v178
	v_mov_b32_e32 v179, v183
	v_mov_b32_e32 v182, v252
	s_lshr_b32 s44, s33, 4
	s_add_i32 s45, s10, s8
	s_cmp_lt_u32 s45, 0x800
	s_cbranch_scc1 .Latt_newunit
	s_mov_b32 s37, 1
	s_branch .Latt_ud_done
